# v40 plus phase-10 SS row-scale loads hoisted (one wait instead of eight) and phase-8 SS atomics deferred to the tile-epilogue end
# baseline (speedup 1.0000x reference)
; __device__ __forceinline__ float bf_lo(unsigned w) { return __uint_as_float(w << 16); }
;     __device__ __forceinline__ void operator()(const f32x4 (&acc)[2][2][4][2], const Unit& u, int wr, int wc, int fr, int fq) const {
;         const int row0 = u.pm * BM + wr * 64 + fr; const int col0 = u.pn * BM + wc * 32 + 8 * fq;
;         float gp[2][8];
;         if (MODE == 2) {
; #pragma unroll
;             for (int bj = 0; bj < 2; ++bj) { const f32x4 g0 = *(const f32x4*)(gpre + col0 + bj * HALF), g1 = *(const f32x4*)(gpre + col0 + bj * HALF + 4);
; #pragma unroll
;                 for (int e = 0; e < 4; ++e) { gp[bj][e] = g0[e]; gp[bj][4 + e] = g1[e]; } }
;         }
; #pragma unroll
;         for (int ai = 0; ai < 2; ++ai)
; #pragma unroll
;             for (int m = 0; m < 4; ++m) { const int row = row0 + ai * HALF + m * 16; const size_t off = (size_t)row * 1024 + col0; float rs = 0.f;
; #pragma unroll
;                 for (int bj = 0; bj < 2; ++bj) { const size_t c = off + bj * HALF;
;                     const u32x4 hw = *(const u32x4*)(Hin + c); const u32x4 pw = *(const u32x4*)(PP + c);
;                     float o[8];
; #pragma unroll
;                     for (int n = 0; n < 2; ++n)
; #pragma unroll
;                         for (int w = 0; w < 2; ++w) { const unsigned hh = hw[2 * n + w], pp = pw[2 * n + w]; const f32x4 a = acc[ai][bj][m][n];
;                             o[4 * n + 2 * w] = bf_lo(hh) + bf_lo(pp) * sigmoid_f(a[2 * w]); o[4 * n + 2 * w + 1] = bf_hi(hh) + bf_hi(pp) * sigmoid_f(a[2 * w + 1]); }
;                     if (MODE == 1) { *(f32x4*)(Fout + c) = (f32x4){o[0], o[1], o[2], o[3]}; *(f32x4*)(Fout + c + 4) = (f32x4){o[4], o[5], o[6], o[7]}; }
;                     else { u32x4 w; w.x = cvt_pk_bf16(o[0], o[1]); w.y = cvt_pk_bf16(o[2], o[3]); w.z = cvt_pk_bf16(o[4], o[5]); w.w = cvt_pk_bf16(o[6], o[7]); *(u32x4*)(Hout + c) = w; }
;                     if (MODE == 2) {
; #pragma unroll
;                         for (int e = 0; e < 8; ++e) rs += o[e] * o[e];
;                         u32x4 w; w.x = cvt_pk_bf16(o[0] * gp[bj][0], o[1] * gp[bj][1]); w.y = cvt_pk_bf16(o[2] * gp[bj][2], o[3] * gp[bj][3]);
;                         w.z = cvt_pk_bf16(o[4] * gp[bj][4], o[5] * gp[bj][5]); w.w = cvt_pk_bf16(o[6] * gp[bj][6], o[7] * gp[bj][7]); *(u32x4*)(A2 + c) = w; } }
.LBB0_839:
	v_lshl_add_u32 v154, s54, 8, v158
	v_lshl_or_b32 v152, s56, 8, v161
	v_ashrrev_i32_e32 v155, 31, v154
	v_ashrrev_i32_e32 v153, 31, v152
	v_lshlrev_b64 v[48:49], 10, v[154:155]
	v_lshl_add_u64 v[48:49], v[48:49], 0, v[152:153]
	v_lshlrev_b64 v[156:157], 1, v[48:49]
	v_lshl_add_u64 v[174:175], s[16:17], 0, v[156:157]
	v_lshl_add_u64 v[48:49], s[36:37], 0, v[156:157]
	global_load_dwordx4 v[166:169], v[174:175], off
	global_load_dwordx4 v[170:173], v[48:49], off
	v_lshl_add_u64 v[178:179], v[152:153], 2, s[14:15]
	global_load_dwordx4 v[52:55], v[178:179], off
	global_load_dwordx4 v[48:51], v[178:179], off offset:16
	v_mul_f32_e32 v37, 0xbfb8aa3b, v37
	v_mul_f32_e32 v38, 0xbfb8aa3b, v38
	v_mul_f32_e32 v44, 0xbfb8aa3b, v44
	v_mul_f32_e32 v45, 0xbfb8aa3b, v45
	v_mul_f32_e32 v46, 0xbfb8aa3b, v46
	v_mul_f32_e32 v47, 0xbfb8aa3b, v47
	v_mul_f32_e32 v36, 0xbfb8aa3b, v36
	v_mul_f32_e32 v39, 0xbfb8aa3b, v39
	v_exp_f32_e32 v184, v37
	v_exp_f32_e32 v185, v38
	v_exp_f32_e32 v177, v44
	v_exp_f32_e32 v180, v45
	v_exp_f32_e32 v181, v46
	v_exp_f32_e32 v182, v47
	v_exp_f32_e32 v183, v36
	v_exp_f32_e32 v186, v39
	v_add_f32_e32 v184, 1.0, v184
	v_add_f32_e32 v185, 1.0, v185
	global_load_dwordx4 v[36:39], v[178:179], off offset:528
	global_load_dwordx4 v[44:47], v[178:179], off offset:512
	v_add_f32_e32 v177, 1.0, v177
	v_add_f32_e32 v178, 1.0, v180
	v_add_f32_e32 v179, 1.0, v181
	v_add_f32_e32 v180, 1.0, v182
	v_add_f32_e32 v181, 1.0, v183
	v_add_f32_e32 v186, 1.0, v186
	v_rcp_f32_e32 v184, v184
	v_rcp_f32_e32 v185, v185
	v_rcp_f32_e32 v177, v177
	v_rcp_f32_e32 v178, v178
	v_rcp_f32_e32 v179, v179
	v_rcp_f32_e32 v180, v180
	v_rcp_f32_e32 v181, v181
	v_rcp_f32_e32 v186, v186
	v_lshl_add_u64 v[182:183], s[12:13], 0, v[156:157]
	v_or_b32_e32 v156, 0x100, v156
	v_mul_f32_e32 v132, 0xbfb8aa3b, v132
	v_mul_f32_e32 v133, 0xbfb8aa3b, v133
	v_exp_f32_e32 v132, v132
	v_mul_f32_e32 v134, 0xbfb8aa3b, v134
	v_exp_f32_e32 v133, v133
	v_mul_f32_e32 v135, 0xbfb8aa3b, v135
	v_mul_f32_e32 v128, 0xbfb8aa3b, v128
	v_mul_f32_e32 v129, 0xbfb8aa3b, v129
	v_exp_f32_e32 v134, v134
	v_mul_f32_e32 v130, 0xbfb8aa3b, v130
	v_mul_f32_e32 v131, 0xbfb8aa3b, v131
	v_exp_f32_e32 v135, v135
	v_exp_f32_e32 v128, v128
	v_exp_f32_e32 v129, v129
	v_exp_f32_e32 v130, v130
	v_exp_f32_e32 v131, v131
	v_add_f32_e32 v132, 1.0, v132
	v_add_f32_e32 v133, 1.0, v133
	v_rcp_f32_e32 v132, v132
	v_add_f32_e32 v134, 1.0, v134
	v_rcp_f32_e32 v133, v133
	v_add_f32_e32 v135, 1.0, v135
	v_add_f32_e32 v128, 1.0, v128
	v_add_f32_e32 v129, 1.0, v129
	v_rcp_f32_e32 v134, v134
	v_add_f32_e32 v130, 1.0, v130
	v_add_f32_e32 v131, 1.0, v131
	v_rcp_f32_e32 v135, v135
	v_rcp_f32_e32 v128, v128
	v_rcp_f32_e32 v129, v129
	v_rcp_f32_e32 v130, v130
	v_rcp_f32_e32 v131, v131
	s_waitcnt vmcnt(0)
	v_lshlrev_b32_e32 v187, 16, v166
	v_lshlrev_b32_e32 v188, 16, v170
	v_and_b32_e32 v189, 0xffff0000, v166
	v_and_b32_e32 v166, 0xffff0000, v170
	v_lshlrev_b32_e32 v190, 16, v167
	v_lshlrev_b32_e32 v170, 16, v171
	v_and_b32_e32 v191, 0xffff0000, v167
	v_and_b32_e32 v167, 0xffff0000, v171
	v_lshlrev_b32_e32 v192, 16, v168
	v_lshlrev_b32_e32 v171, 16, v172
	v_and_b32_e32 v193, 0xffff0000, v168
	v_and_b32_e32 v168, 0xffff0000, v172
	v_lshlrev_b32_e32 v194, 16, v169
	v_lshlrev_b32_e32 v172, 16, v173
	v_and_b32_e32 v195, 0xffff0000, v169
	v_and_b32_e32 v169, 0xffff0000, v173
	v_fmac_f32_e32 v193, v184, v168
	v_fmac_f32_e32 v194, v185, v172
	v_fmac_f32_e32 v187, v177, v188
	v_fmac_f32_e32 v189, v178, v166
	v_fmac_f32_e32 v190, v179, v170
	v_fmac_f32_e32 v191, v180, v167
	v_fmac_f32_e32 v192, v181, v171
	v_fmac_f32_e32 v195, v186, v169
	v_cvt_pk_bf16_f32 v166, v187, v189
	v_cvt_pk_bf16_f32 v167, v190, v191
	v_cvt_pk_bf16_f32 v168, v192, v193
	v_cvt_pk_bf16_f32 v169, v194, v195
	v_mul_f32_e32 v178, v49, v193
	v_mul_f32_e32 v179, v50, v194
	v_mul_f32_e32 v170, v52, v187
	v_mul_f32_e32 v171, v53, v189
	v_mul_f32_e32 v172, v54, v190
	v_mul_f32_e32 v173, v55, v191
	v_mul_f32_e32 v177, v48, v192
	v_mul_f32_e32 v180, v51, v195
	global_store_dwordx4 v[174:175], v[166:169], off
	v_lshl_add_u64 v[174:175], s[16:17], 0, v[156:157]
	s_nop 0
	v_cvt_pk_bf16_f32 v166, v170, v171
	v_cvt_pk_bf16_f32 v167, v172, v173
	v_cvt_pk_bf16_f32 v168, v177, v178
	v_cvt_pk_bf16_f32 v169, v179, v180
	v_lshl_add_u64 v[178:179], s[36:37], 0, v[156:157]
	global_load_dwordx4 v[170:173], v[174:175], off
	s_nop 0
	global_load_dwordx4 v[178:181], v[178:179], off
	v_mul_f32_e32 v177, v189, v189
	v_fmac_f32_e32 v177, v187, v187
	v_fmac_f32_e32 v177, v190, v190
	v_fmac_f32_e32 v177, v191, v191
	v_fmac_f32_e32 v177, v192, v192
	v_fmac_f32_e32 v177, v193, v193
	global_store_dwordx4 v[182:183], v[166:169], off
	v_fmac_f32_e32 v177, v194, v194
	v_fmac_f32_e32 v177, v195, v195
	s_waitcnt vmcnt(2)
	v_lshlrev_b32_e32 v166, 16, v170
	s_waitcnt vmcnt(1)
; __device__ __forceinline__ unsigned cvt_pk_bf16(float lo, float hi) { unsigned r; asm volatile("v_cvt_pk_bf16_f32 %0, %1, %2" : "=v"(r) : "v"(lo), "v"(hi)); return r; }
; __device__ __forceinline__ float bf_lo(unsigned w) { return __uint_as_float(w << 16); }
; __device__ __forceinline__ float bf_hi(unsigned w) { return __uint_as_float(w & 0xffff0000u); }
; __device__ __forceinline__ float sigmoid_f(float x) { return __builtin_amdgcn_rcpf(1.0f + __builtin_amdgcn_exp2f(-1.4426950408889634f * x)); }
;     __device__ __forceinline__ void operator()(const f32x4 (&acc)[2][2][4][2], const Unit& u, int wr, int wc, int fr, int fq) const {
;     ...
;                     const u32x4 hw = *(const u32x4*)(Hin + c); const u32x4 pw = *(const u32x4*)(PP + c);
;                     float o[8];
; #pragma unroll
;                     for (int n = 0; n < 2; ++n)
; #pragma unroll
;                         for (int w = 0; w < 2; ++w) { const unsigned hh = hw[2 * n + w], pp = pw[2 * n + w]; const f32x4 a = acc[ai][bj][m][n];
;                             o[4 * n + 2 * w] = bf_lo(hh) + bf_lo(pp) * sigmoid_f(a[2 * w]); o[4 * n + 2 * w + 1] = bf_hi(hh) + bf_hi(pp) * sigmoid_f(a[2 * w + 1]); }
;                     if (MODE == 1) { *(f32x4*)(Fout + c) = (f32x4){o[0], o[1], o[2], o[3]}; *(f32x4*)(Fout + c + 4) = (f32x4){o[4], o[5], o[6], o[7]}; }
;                     else { u32x4 w; w.x = cvt_pk_bf16(o[0], o[1]); w.y = cvt_pk_bf16(o[2], o[3]); w.z = cvt_pk_bf16(o[4], o[5]); w.w = cvt_pk_bf16(o[6], o[7]); *(u32x4*)(Hout + c) = w; }
;                     if (MODE == 2) {
; #pragma unroll
;                         for (int e = 0; e < 8; ++e) rs += o[e] * o[e];
;                         u32x4 w; w.x = cvt_pk_bf16(o[0] * gp[bj][0], o[1] * gp[bj][1]); w.y = cvt_pk_bf16(o[2] * gp[bj][2], o[3] * gp[bj][3]);
;                         w.z = cvt_pk_bf16(o[4] * gp[bj][4], o[5] * gp[bj][5]); w.w = cvt_pk_bf16(o[6] * gp[bj][6], o[7] * gp[bj][7]); *(u32x4*)(A2 + c) = w; } }
;                 if (MODE == 2) { rs += __shfl_xor(rs, 16); rs += __shfl_xor(rs, 32); if (fq == 0) atomicAdd(SS + row, rs); } }
	v_lshlrev_b32_e32 v167, 16, v178
	v_and_b32_e32 v168, 0xffff0000, v170
	v_and_b32_e32 v169, 0xffff0000, v178
	v_fmac_f32_e32 v166, v132, v167
	v_lshlrev_b32_e32 v170, 16, v171
	v_lshlrev_b32_e32 v178, 16, v179
	v_fmac_f32_e32 v168, v133, v169
	v_fmac_f32_e32 v177, v166, v166
	v_and_b32_e32 v171, 0xffff0000, v171
	v_and_b32_e32 v179, 0xffff0000, v179
	v_lshlrev_b32_e32 v182, 16, v172
	v_lshlrev_b32_e32 v183, 16, v180
	v_and_b32_e32 v172, 0xffff0000, v172
	v_and_b32_e32 v180, 0xffff0000, v180
	v_fmac_f32_e32 v170, v134, v178
	v_fmac_f32_e32 v177, v168, v168
	v_lshlrev_b32_e32 v184, 16, v173
	v_lshlrev_b32_e32 v185, 16, v181
	v_and_b32_e32 v173, 0xffff0000, v173
	v_and_b32_e32 v181, 0xffff0000, v181
	v_fmac_f32_e32 v171, v135, v179
	v_fmac_f32_e32 v182, v128, v183
	v_fmac_f32_e32 v172, v129, v180
	v_cvt_pk_bf16_f32 v128, v166, v168
	v_cvt_pk_bf16_f32 v129, v170, v171
	v_fmac_f32_e32 v177, v170, v170
	v_fmac_f32_e32 v184, v130, v185
	v_fmac_f32_e32 v173, v131, v181
	v_cvt_pk_bf16_f32 v130, v182, v172
	v_cvt_pk_bf16_f32 v131, v184, v173
	global_store_dwordx4 v[174:175], v[128:131], off
	v_fmac_f32_e32 v177, v171, v171
	v_fmac_f32_e32 v177, v182, v182
	v_and_b32_e32 v129, 64, v165
	v_xor_b32_e32 v128, 16, v165
	v_add_u32_e32 v129, 64, v129
	v_fmac_f32_e32 v177, v172, v172
	v_cmp_lt_i32_e32 vcc, v128, v129
	v_mul_f32_e32 v132, v44, v166
	v_fmac_f32_e32 v177, v184, v184
	v_cndmask_b32_e32 v128, v165, v128, vcc
	v_mul_f32_e32 v133, v45, v168
	v_cvt_pk_bf16_f32 v166, v132, v133
	v_fmac_f32_e32 v177, v173, v173
	v_lshlrev_b32_e32 v132, 2, v128
	ds_bpermute_b32 v128, v132, v177
	v_mul_f32_e32 v131, v37, v172
	v_mul_f32_e32 v134, v46, v170
	v_mul_f32_e32 v135, v47, v171
	v_cvt_pk_bf16_f32 v167, v134, v135
	v_mul_f32_e32 v130, v36, v182
	v_cvt_pk_bf16_f32 v168, v130, v131
	v_xor_b32_e32 v131, 32, v165
	v_cmp_lt_i32_e32 vcc, v131, v129
	s_waitcnt lgkmcnt(0)
	v_add_f32_e32 v128, v177, v128
	v_mul_f32_e32 v130, v38, v184
	v_cndmask_b32_e32 v129, v165, v131, vcc
	v_lshlrev_b32_e32 v133, 2, v129
	ds_bpermute_b32 v129, v133, v128
	v_mul_f32_e32 v131, v39, v173
	v_cvt_pk_bf16_f32 v169, v130, v131
	v_lshl_add_u64 v[130:131], s[12:13], 0, v[156:157]
	global_store_dwordx4 v[130:131], v[166:169], off
	s_and_saveexec_b64 s[54:55], s[4:5]
	s_cbranch_execz .LBB0_841
	v_lshl_add_u64 v[130:131], v[154:155], 2, s[18:19]
	s_waitcnt lgkmcnt(0)
	v_add_f32_e32 v128, v128, v129
	v_mov_b32_e32 v230, v128
	v_lshl_add_u64 v[228:229], v[154:155], 2, s[18:19]
.LBB0_841:
	s_or_b64 exec, exec, s[54:55]
	v_or_b32_e32 v128, 16, v154
	s_waitcnt lgkmcnt(0)
	v_ashrrev_i32_e32 v129, 31, v128
	v_lshlrev_b64 v[130:131], 10, v[128:129]
	v_lshl_add_u64 v[130:131], v[130:131], 0, v[152:153]
	v_lshlrev_b64 v[130:131], 1, v[130:131]
	v_lshl_add_u64 v[134:135], s[16:17], 0, v[130:131]
	v_lshl_add_u64 v[156:157], s[36:37], 0, v[130:131]
	global_load_dwordx4 v[166:169], v[134:135], off
	global_load_dwordx4 v[170:173], v[156:157], off
	v_mul_f32_e32 v124, 0xbfb8aa3b, v124
	v_mul_f32_e32 v125, 0xbfb8aa3b, v125
	v_mul_f32_e32 v126, 0xbfb8aa3b, v126
	v_mul_f32_e32 v127, 0xbfb8aa3b, v127
	v_mul_f32_e32 v120, 0xbfb8aa3b, v120
	v_mul_f32_e32 v121, 0xbfb8aa3b, v121
	v_mul_f32_e32 v122, 0xbfb8aa3b, v122
	v_mul_f32_e32 v123, 0xbfb8aa3b, v123
	v_exp_f32_e32 v124, v124
	v_exp_f32_e32 v125, v125
	v_exp_f32_e32 v126, v126
	v_exp_f32_e32 v127, v127
	v_exp_f32_e32 v120, v120
	v_exp_f32_e32 v121, v121
	v_exp_f32_e32 v122, v122
	v_exp_f32_e32 v123, v123
	v_add_f32_e32 v124, 1.0, v124
	v_add_f32_e32 v125, 1.0, v125
	v_add_f32_e32 v126, 1.0, v126
	v_add_f32_e32 v127, 1.0, v127
	v_add_f32_e32 v120, 1.0, v120
	v_add_f32_e32 v121, 1.0, v121
	v_add_f32_e32 v122, 1.0, v122
	v_add_f32_e32 v123, 1.0, v123
	v_rcp_f32_e32 v124, v124
	v_rcp_f32_e32 v125, v125
	v_rcp_f32_e32 v126, v126
	v_rcp_f32_e32 v127, v127
	v_rcp_f32_e32 v120, v120
	v_rcp_f32_e32 v121, v121
	v_rcp_f32_e32 v122, v122
	v_rcp_f32_e32 v123, v123
	v_lshl_add_u64 v[156:157], s[12:13], 0, v[130:131]
	v_or_b32_e32 v130, 0x100, v130
	v_lshl_add_u64 v[174:175], s[16:17], 0, v[130:131]
	v_lshl_add_u64 v[178:179], s[36:37], 0, v[130:131]
	v_mul_f32_e32 v116, 0xbfb8aa3b, v116
	v_mul_f32_e32 v117, 0xbfb8aa3b, v117
	v_exp_f32_e32 v116, v116
	v_mul_f32_e32 v118, 0xbfb8aa3b, v118
	v_exp_f32_e32 v117, v117
	v_mul_f32_e32 v119, 0xbfb8aa3b, v119
	v_exp_f32_e32 v118, v118
	v_mul_f32_e32 v112, 0xbfb8aa3b, v112
	v_exp_f32_e32 v119, v119
	v_mul_f32_e32 v113, 0xbfb8aa3b, v113
	v_exp_f32_e32 v112, v112
	v_add_f32_e32 v116, 1.0, v116
	v_mul_f32_e32 v114, 0xbfb8aa3b, v114
	v_exp_f32_e32 v113, v113
	v_add_f32_e32 v117, 1.0, v117
	v_rcp_f32_e32 v116, v116
	v_mul_f32_e32 v115, 0xbfb8aa3b, v115
	v_exp_f32_e32 v114, v114
	v_add_f32_e32 v118, 1.0, v118
	v_rcp_f32_e32 v117, v117
	v_exp_f32_e32 v115, v115
	v_add_f32_e32 v119, 1.0, v119
	v_rcp_f32_e32 v118, v118
	v_add_f32_e32 v112, 1.0, v112
	v_rcp_f32_e32 v119, v119
	v_add_f32_e32 v113, 1.0, v113
	v_rcp_f32_e32 v112, v112
	v_add_f32_e32 v114, 1.0, v114
	v_rcp_f32_e32 v113, v113
	v_add_f32_e32 v115, 1.0, v115
	v_rcp_f32_e32 v114, v114
	v_rcp_f32_e32 v115, v115
	s_waitcnt vmcnt(1)
	v_lshlrev_b32_e32 v155, 16, v166
	s_waitcnt vmcnt(0)
; __device__ __forceinline__ unsigned cvt_pk_bf16(float lo, float hi) { unsigned r; asm volatile("v_cvt_pk_bf16_f32 %0, %1, %2" : "=v"(r) : "v"(lo), "v"(hi)); return r; }
; __device__ __forceinline__ float bf_lo(unsigned w) { return __uint_as_float(w << 16); }
; __device__ __forceinline__ float bf_hi(unsigned w) { return __uint_as_float(w & 0xffff0000u); }
; __device__ __forceinline__ float sigmoid_f(float x) { return __builtin_amdgcn_rcpf(1.0f + __builtin_amdgcn_exp2f(-1.4426950408889634f * x)); }
;     __device__ __forceinline__ void operator()(const f32x4 (&acc)[2][2][4][2], const Unit& u, int wr, int wc, int fr, int fq) const {
;     ...
;             for (int m = 0; m < 4; ++m) { const int row = row0 + ai * HALF + m * 16; const size_t off = (size_t)row * 1024 + col0; float rs = 0.f;
; #pragma unroll
;                 for (int bj = 0; bj < 2; ++bj) { const size_t c = off + bj * HALF;
;                     const u32x4 hw = *(const u32x4*)(Hin + c); const u32x4 pw = *(const u32x4*)(PP + c);
;                     float o[8];
; #pragma unroll
;                     for (int n = 0; n < 2; ++n)
; #pragma unroll
;                         for (int w = 0; w < 2; ++w) { const unsigned hh = hw[2 * n + w], pp = pw[2 * n + w]; const f32x4 a = acc[ai][bj][m][n];
;                             o[4 * n + 2 * w] = bf_lo(hh) + bf_lo(pp) * sigmoid_f(a[2 * w]); o[4 * n + 2 * w + 1] = bf_hi(hh) + bf_hi(pp) * sigmoid_f(a[2 * w + 1]); }
;                     if (MODE == 1) { *(f32x4*)(Fout + c) = (f32x4){o[0], o[1], o[2], o[3]}; *(f32x4*)(Fout + c + 4) = (f32x4){o[4], o[5], o[6], o[7]}; }
;                     else { u32x4 w; w.x = cvt_pk_bf16(o[0], o[1]); w.y = cvt_pk_bf16(o[2], o[3]); w.z = cvt_pk_bf16(o[4], o[5]); w.w = cvt_pk_bf16(o[6], o[7]); *(u32x4*)(Hout + c) = w; }
;                     if (MODE == 2) {
; #pragma unroll
;                         for (int e = 0; e < 8; ++e) rs += o[e] * o[e];
;                         u32x4 w; w.x = cvt_pk_bf16(o[0] * gp[bj][0], o[1] * gp[bj][1]); w.y = cvt_pk_bf16(o[2] * gp[bj][2], o[3] * gp[bj][3]);
;                         w.z = cvt_pk_bf16(o[4] * gp[bj][4], o[5] * gp[bj][5]); w.w = cvt_pk_bf16(o[6] * gp[bj][6], o[7] * gp[bj][7]); *(u32x4*)(A2 + c) = w; } }
;                 if (MODE == 2) { rs += __shfl_xor(rs, 16); rs += __shfl_xor(rs, 32); if (fq == 0) atomicAdd(SS + row, rs); } }
	v_lshlrev_b32_e32 v177, 16, v170
	v_and_b32_e32 v180, 0xffff0000, v166
	v_and_b32_e32 v166, 0xffff0000, v170
	v_lshlrev_b32_e32 v170, 16, v167
	v_lshlrev_b32_e32 v181, 16, v171
	v_and_b32_e32 v182, 0xffff0000, v167
	v_and_b32_e32 v167, 0xffff0000, v171
	v_lshlrev_b32_e32 v171, 16, v168
	v_lshlrev_b32_e32 v183, 16, v172
	v_and_b32_e32 v184, 0xffff0000, v168
	v_and_b32_e32 v168, 0xffff0000, v172
	v_lshlrev_b32_e32 v172, 16, v169
	v_lshlrev_b32_e32 v185, 16, v173
	v_and_b32_e32 v186, 0xffff0000, v169
	v_and_b32_e32 v169, 0xffff0000, v173
	v_fmac_f32_e32 v155, v124, v177
	v_fmac_f32_e32 v180, v125, v166
	v_fmac_f32_e32 v170, v126, v181
	v_fmac_f32_e32 v182, v127, v167
	v_fmac_f32_e32 v171, v120, v183
	v_fmac_f32_e32 v184, v121, v168
	v_fmac_f32_e32 v172, v122, v185
	v_fmac_f32_e32 v186, v123, v169
	v_cvt_pk_bf16_f32 v120, v155, v180
	v_cvt_pk_bf16_f32 v121, v170, v182
	v_cvt_pk_bf16_f32 v122, v171, v184
	v_cvt_pk_bf16_f32 v123, v172, v186
	v_mul_f32_e32 v124, v52, v155
	v_mul_f32_e32 v125, v53, v180
	v_mul_f32_e32 v126, v54, v170
	v_mul_f32_e32 v127, v55, v182
	v_mul_f32_e32 v166, v48, v171
	v_mul_f32_e32 v167, v49, v184
	v_mul_f32_e32 v168, v50, v172
	v_mul_f32_e32 v169, v51, v186
	global_store_dwordx4 v[134:135], v[120:123], off
	v_mul_f32_e32 v134, v180, v180
	v_fmac_f32_e32 v134, v155, v155
	v_cvt_pk_bf16_f32 v120, v124, v125
	v_cvt_pk_bf16_f32 v121, v126, v127
	v_cvt_pk_bf16_f32 v122, v166, v167
	v_cvt_pk_bf16_f32 v123, v168, v169
	global_load_dwordx4 v[124:127], v[174:175], off
	global_load_dwordx4 v[166:169], v[178:179], off
	v_fmac_f32_e32 v134, v170, v170
	v_fmac_f32_e32 v134, v182, v182
	v_fmac_f32_e32 v134, v171, v171
	v_fmac_f32_e32 v134, v184, v184
	global_store_dwordx4 v[156:157], v[120:123], off
	v_fmac_f32_e32 v134, v172, v172
	v_fmac_f32_e32 v134, v186, v186
	s_waitcnt vmcnt(2)
	v_lshlrev_b32_e32 v120, 16, v124
	s_waitcnt vmcnt(1)
	v_lshlrev_b32_e32 v121, 16, v166
	v_and_b32_e32 v122, 0xffff0000, v124
	v_and_b32_e32 v123, 0xffff0000, v166
	v_fmac_f32_e32 v120, v116, v121
	v_lshlrev_b32_e32 v124, 16, v125
	v_lshlrev_b32_e32 v135, 16, v167
	v_fmac_f32_e32 v122, v117, v123
	v_fmac_f32_e32 v134, v120, v120
	v_and_b32_e32 v125, 0xffff0000, v125
	v_and_b32_e32 v155, 0xffff0000, v167
	v_fmac_f32_e32 v124, v118, v135
	v_fmac_f32_e32 v134, v122, v122
	v_lshlrev_b32_e32 v156, 16, v126
	v_lshlrev_b32_e32 v157, 16, v168
	v_fmac_f32_e32 v125, v119, v155
	v_fmac_f32_e32 v134, v124, v124
	v_and_b32_e32 v126, 0xffff0000, v126
	v_and_b32_e32 v166, 0xffff0000, v168
	v_fmac_f32_e32 v156, v112, v157
	v_fmac_f32_e32 v134, v125, v125
	v_lshlrev_b32_e32 v167, 16, v127
	v_lshlrev_b32_e32 v168, 16, v169
	v_fmac_f32_e32 v126, v113, v166
	v_fmac_f32_e32 v134, v156, v156
	v_and_b32_e32 v127, 0xffff0000, v127
	v_and_b32_e32 v169, 0xffff0000, v169
	v_fmac_f32_e32 v167, v114, v168
	v_fmac_f32_e32 v134, v126, v126
	v_fmac_f32_e32 v127, v115, v169
	v_fmac_f32_e32 v134, v167, v167
	v_cvt_pk_bf16_f32 v112, v120, v122
	v_fmac_f32_e32 v134, v127, v127
	v_cvt_pk_bf16_f32 v113, v124, v125
	v_cvt_pk_bf16_f32 v114, v156, v126
	v_cvt_pk_bf16_f32 v115, v167, v127
	global_store_dwordx4 v[174:175], v[112:115], off
	ds_bpermute_b32 v112, v132, v134
	v_mul_f32_e32 v116, v44, v120
	v_mul_f32_e32 v117, v45, v122
	v_cvt_pk_bf16_f32 v114, v116, v117
	v_mul_f32_e32 v113, v36, v156
	v_mul_f32_e32 v116, v37, v126
	s_waitcnt lgkmcnt(0)
	v_add_f32_e32 v112, v134, v112
	v_mul_f32_e32 v118, v46, v124
	v_mul_f32_e32 v119, v47, v125
	v_cvt_pk_bf16_f32 v115, v118, v119
	v_cvt_pk_bf16_f32 v116, v113, v116
	ds_bpermute_b32 v113, v133, v112
	v_mul_f32_e32 v117, v38, v167
	v_mul_f32_e32 v118, v39, v127
	v_cvt_pk_bf16_f32 v117, v117, v118
	v_lshl_add_u64 v[118:119], s[12:13], 0, v[130:131]
	global_store_dwordx4 v[118:119], v[114:117], off
	s_and_saveexec_b64 s[54:55], s[4:5]
	s_cbranch_execz .LBB0_843
	v_lshl_add_u64 v[114:115], v[128:129], 2, s[18:19]
	s_waitcnt lgkmcnt(0)
	v_add_f32_e32 v112, v112, v113
	v_mov_b32_e32 v231, v112
.LBB0_843:
	s_or_b64 exec, exec, s[54:55]
	v_or_b32_e32 v112, 32, v154
	s_waitcnt lgkmcnt(0)
	v_ashrrev_i32_e32 v113, 31, v112
	v_lshlrev_b64 v[114:115], 10, v[112:113]
	v_lshl_add_u64 v[114:115], v[114:115], 0, v[152:153]
	v_lshlrev_b64 v[114:115], 1, v[114:115]
	v_lshl_add_u64 v[124:125], s[16:17], 0, v[114:115]
	v_lshl_add_u64 v[120:121], s[36:37], 0, v[114:115]
	global_load_dwordx4 v[116:119], v[124:125], off
	s_nop 0
	global_load_dwordx4 v[120:123], v[120:121], off
	v_mul_f32_e32 v108, 0xbfb8aa3b, v108
	v_mul_f32_e32 v109, 0xbfb8aa3b, v109
	v_mul_f32_e32 v110, 0xbfb8aa3b, v110
	v_mul_f32_e32 v111, 0xbfb8aa3b, v111
	v_mul_f32_e32 v104, 0xbfb8aa3b, v104
	v_mul_f32_e32 v105, 0xbfb8aa3b, v105
	v_mul_f32_e32 v106, 0xbfb8aa3b, v106
	v_mul_f32_e32 v107, 0xbfb8aa3b, v107
	v_exp_f32_e32 v108, v108
	v_exp_f32_e32 v109, v109
	v_exp_f32_e32 v110, v110
	v_exp_f32_e32 v111, v111
	v_exp_f32_e32 v104, v104
	v_exp_f32_e32 v105, v105
	v_exp_f32_e32 v106, v106
	v_exp_f32_e32 v107, v107
	v_add_f32_e32 v108, 1.0, v108
	v_add_f32_e32 v109, 1.0, v109
	v_add_f32_e32 v110, 1.0, v110
	v_add_f32_e32 v111, 1.0, v111
	v_add_f32_e32 v104, 1.0, v104
	v_add_f32_e32 v105, 1.0, v105
	v_add_f32_e32 v106, 1.0, v106
	v_add_f32_e32 v107, 1.0, v107
	v_rcp_f32_e32 v108, v108
	v_rcp_f32_e32 v109, v109
	v_rcp_f32_e32 v110, v110
	v_rcp_f32_e32 v111, v111
	v_rcp_f32_e32 v104, v104
	v_rcp_f32_e32 v105, v105
	v_rcp_f32_e32 v106, v106
	v_rcp_f32_e32 v107, v107
	v_lshl_add_u64 v[126:127], s[12:13], 0, v[114:115]
	v_or_b32_e32 v114, 0x100, v114
	v_lshl_add_u64 v[128:129], s[16:17], 0, v[114:115]
	v_lshl_add_u64 v[130:131], s[36:37], 0, v[114:115]
	v_mul_f32_e32 v100, 0xbfb8aa3b, v100
	v_mul_f32_e32 v101, 0xbfb8aa3b, v101
	v_exp_f32_e32 v100, v100
	v_mul_f32_e32 v102, 0xbfb8aa3b, v102
	v_exp_f32_e32 v101, v101
	v_mul_f32_e32 v103, 0xbfb8aa3b, v103
	v_exp_f32_e32 v102, v102
	v_mul_f32_e32 v96, 0xbfb8aa3b, v96
	v_exp_f32_e32 v103, v103
	v_mul_f32_e32 v97, 0xbfb8aa3b, v97
	v_exp_f32_e32 v96, v96
	v_add_f32_e32 v100, 1.0, v100
	v_mul_f32_e32 v98, 0xbfb8aa3b, v98
	v_exp_f32_e32 v97, v97
	v_add_f32_e32 v101, 1.0, v101
	v_rcp_f32_e32 v100, v100
	v_mul_f32_e32 v99, 0xbfb8aa3b, v99
	v_exp_f32_e32 v98, v98
	v_add_f32_e32 v102, 1.0, v102
	v_rcp_f32_e32 v101, v101
	v_exp_f32_e32 v99, v99
	v_add_f32_e32 v103, 1.0, v103
	v_rcp_f32_e32 v102, v102
	v_add_f32_e32 v96, 1.0, v96
	v_rcp_f32_e32 v103, v103
	v_add_f32_e32 v97, 1.0, v97
	v_rcp_f32_e32 v96, v96
	v_add_f32_e32 v98, 1.0, v98
	v_rcp_f32_e32 v97, v97
	v_add_f32_e32 v99, 1.0, v99
	v_rcp_f32_e32 v98, v98
	v_rcp_f32_e32 v99, v99
	s_waitcnt vmcnt(1)
; __device__ __forceinline__ unsigned cvt_pk_bf16(float lo, float hi) { unsigned r; asm volatile("v_cvt_pk_bf16_f32 %0, %1, %2" : "=v"(r) : "v"(lo), "v"(hi)); return r; }
; __device__ __forceinline__ float bf_lo(unsigned w) { return __uint_as_float(w << 16); }
; __device__ __forceinline__ float bf_hi(unsigned w) { return __uint_as_float(w & 0xffff0000u); }
; __device__ __forceinline__ float sigmoid_f(float x) { return __builtin_amdgcn_rcpf(1.0f + __builtin_amdgcn_exp2f(-1.4426950408889634f * x)); }
;     __device__ __forceinline__ void operator()(const f32x4 (&acc)[2][2][4][2], const Unit& u, int wr, int wc, int fr, int fq) const {
;     ...
;             for (int m = 0; m < 4; ++m) { const int row = row0 + ai * HALF + m * 16; const size_t off = (size_t)row * 1024 + col0; float rs = 0.f;
; #pragma unroll
;                 for (int bj = 0; bj < 2; ++bj) { const size_t c = off + bj * HALF;
;                     const u32x4 hw = *(const u32x4*)(Hin + c); const u32x4 pw = *(const u32x4*)(PP + c);
;                     float o[8];
; #pragma unroll
;                     for (int n = 0; n < 2; ++n)
; #pragma unroll
;                         for (int w = 0; w < 2; ++w) { const unsigned hh = hw[2 * n + w], pp = pw[2 * n + w]; const f32x4 a = acc[ai][bj][m][n];
;                             o[4 * n + 2 * w] = bf_lo(hh) + bf_lo(pp) * sigmoid_f(a[2 * w]); o[4 * n + 2 * w + 1] = bf_hi(hh) + bf_hi(pp) * sigmoid_f(a[2 * w + 1]); }
;                     if (MODE == 1) { *(f32x4*)(Fout + c) = (f32x4){o[0], o[1], o[2], o[3]}; *(f32x4*)(Fout + c + 4) = (f32x4){o[4], o[5], o[6], o[7]}; }
;                     else { u32x4 w; w.x = cvt_pk_bf16(o[0], o[1]); w.y = cvt_pk_bf16(o[2], o[3]); w.z = cvt_pk_bf16(o[4], o[5]); w.w = cvt_pk_bf16(o[6], o[7]); *(u32x4*)(Hout + c) = w; }
;                     if (MODE == 2) {
; #pragma unroll
;                         for (int e = 0; e < 8; ++e) rs += o[e] * o[e];
;                         u32x4 w; w.x = cvt_pk_bf16(o[0] * gp[bj][0], o[1] * gp[bj][1]); w.y = cvt_pk_bf16(o[2] * gp[bj][2], o[3] * gp[bj][3]);
;                         w.z = cvt_pk_bf16(o[4] * gp[bj][4], o[5] * gp[bj][5]); w.w = cvt_pk_bf16(o[6] * gp[bj][6], o[7] * gp[bj][7]); *(u32x4*)(A2 + c) = w; } }
;                 if (MODE == 2) { rs += __shfl_xor(rs, 16); rs += __shfl_xor(rs, 32); if (fq == 0) atomicAdd(SS + row, rs); } }
	v_lshlrev_b32_e32 v134, 16, v116
	s_waitcnt vmcnt(0)
	v_lshlrev_b32_e32 v135, 16, v120
	v_and_b32_e32 v155, 0xffff0000, v116
	v_and_b32_e32 v116, 0xffff0000, v120
	v_lshlrev_b32_e32 v120, 16, v117
	v_lshlrev_b32_e32 v156, 16, v121
	v_and_b32_e32 v157, 0xffff0000, v117
	v_and_b32_e32 v117, 0xffff0000, v121
	v_lshlrev_b32_e32 v121, 16, v118
	v_lshlrev_b32_e32 v166, 16, v122
	v_and_b32_e32 v167, 0xffff0000, v118
	v_and_b32_e32 v118, 0xffff0000, v122
	v_lshlrev_b32_e32 v122, 16, v119
	v_lshlrev_b32_e32 v168, 16, v123
	v_and_b32_e32 v169, 0xffff0000, v119
	v_and_b32_e32 v119, 0xffff0000, v123
	v_fmac_f32_e32 v134, v108, v135
	v_fmac_f32_e32 v155, v109, v116
	v_fmac_f32_e32 v120, v110, v156
	v_fmac_f32_e32 v157, v111, v117
	v_fmac_f32_e32 v121, v104, v166
	v_fmac_f32_e32 v167, v105, v118
	v_fmac_f32_e32 v122, v106, v168
	v_fmac_f32_e32 v169, v107, v119
	v_cvt_pk_bf16_f32 v104, v134, v155
	v_cvt_pk_bf16_f32 v105, v120, v157
	v_cvt_pk_bf16_f32 v106, v121, v167
	v_cvt_pk_bf16_f32 v107, v122, v169
	v_mul_f32_e32 v108, v52, v134
	v_mul_f32_e32 v109, v53, v155
	v_mul_f32_e32 v110, v54, v120
	v_mul_f32_e32 v111, v55, v157
	v_mul_f32_e32 v116, v48, v121
	v_mul_f32_e32 v117, v49, v167
	v_mul_f32_e32 v118, v50, v122
	v_mul_f32_e32 v119, v51, v169
	global_store_dwordx4 v[124:125], v[104:107], off
	v_mul_f32_e32 v123, v155, v155
	v_fmac_f32_e32 v123, v134, v134
	v_cvt_pk_bf16_f32 v104, v108, v109
	v_cvt_pk_bf16_f32 v105, v110, v111
	v_cvt_pk_bf16_f32 v106, v116, v117
	v_cvt_pk_bf16_f32 v107, v118, v119
	global_load_dwordx4 v[108:111], v[128:129], off
	global_load_dwordx4 v[116:119], v[130:131], off
	v_fmac_f32_e32 v123, v120, v120
	v_fmac_f32_e32 v123, v157, v157
	v_fmac_f32_e32 v123, v121, v121
	v_fmac_f32_e32 v123, v167, v167
	global_store_dwordx4 v[126:127], v[104:107], off
	v_fmac_f32_e32 v123, v122, v122
	v_fmac_f32_e32 v123, v169, v169
	s_waitcnt vmcnt(2)
	v_lshlrev_b32_e32 v104, 16, v108
	s_waitcnt vmcnt(1)
	v_lshlrev_b32_e32 v105, 16, v116
	v_and_b32_e32 v106, 0xffff0000, v108
	v_and_b32_e32 v107, 0xffff0000, v116
	v_fmac_f32_e32 v104, v100, v105
	v_lshlrev_b32_e32 v108, 16, v109
	v_lshlrev_b32_e32 v116, 16, v117
	v_fmac_f32_e32 v106, v101, v107
	v_fmac_f32_e32 v123, v104, v104
	v_and_b32_e32 v109, 0xffff0000, v109
	v_and_b32_e32 v117, 0xffff0000, v117
	v_fmac_f32_e32 v108, v102, v116
	v_fmac_f32_e32 v123, v106, v106
	v_lshlrev_b32_e32 v120, 16, v110
	v_lshlrev_b32_e32 v121, 16, v118
	v_fmac_f32_e32 v109, v103, v117
	v_fmac_f32_e32 v123, v108, v108
	v_and_b32_e32 v110, 0xffff0000, v110
	v_and_b32_e32 v118, 0xffff0000, v118
	v_fmac_f32_e32 v120, v96, v121
	v_fmac_f32_e32 v123, v109, v109
	v_lshlrev_b32_e32 v122, 16, v111
	v_lshlrev_b32_e32 v124, 16, v119
	v_fmac_f32_e32 v110, v97, v118
	v_fmac_f32_e32 v123, v120, v120
	v_and_b32_e32 v111, 0xffff0000, v111
	v_and_b32_e32 v119, 0xffff0000, v119
	v_fmac_f32_e32 v122, v98, v124
	v_fmac_f32_e32 v123, v110, v110
	v_fmac_f32_e32 v111, v99, v119
	v_fmac_f32_e32 v123, v122, v122
	v_cvt_pk_bf16_f32 v96, v104, v106
	v_fmac_f32_e32 v123, v111, v111
	v_cvt_pk_bf16_f32 v97, v108, v109
	v_cvt_pk_bf16_f32 v98, v120, v110
	v_cvt_pk_bf16_f32 v99, v122, v111
	global_store_dwordx4 v[128:129], v[96:99], off
	ds_bpermute_b32 v96, v132, v123
	v_mul_f32_e32 v100, v44, v104
	v_mul_f32_e32 v101, v45, v106
	v_cvt_pk_bf16_f32 v98, v100, v101
	v_mul_f32_e32 v97, v36, v120
	v_mul_f32_e32 v100, v37, v110
	s_waitcnt lgkmcnt(0)
	v_add_f32_e32 v96, v123, v96
	v_mul_f32_e32 v102, v46, v108
	v_mul_f32_e32 v103, v47, v109
	v_cvt_pk_bf16_f32 v99, v102, v103
	v_cvt_pk_bf16_f32 v100, v97, v100
	ds_bpermute_b32 v97, v133, v96
	v_mul_f32_e32 v101, v38, v122
	v_mul_f32_e32 v102, v39, v111
	v_cvt_pk_bf16_f32 v101, v101, v102
	v_lshl_add_u64 v[102:103], s[12:13], 0, v[114:115]
	global_store_dwordx4 v[102:103], v[98:101], off
	s_and_saveexec_b64 s[54:55], s[4:5]
	s_cbranch_execz .LBB0_845
	v_lshl_add_u64 v[98:99], v[112:113], 2, s[18:19]
	s_waitcnt lgkmcnt(0)
	v_add_f32_e32 v96, v96, v97
	v_mov_b32_e32 v232, v96
.LBB0_845:
	s_or_b64 exec, exec, s[54:55]
	v_or_b32_e32 v96, 48, v154
	s_waitcnt lgkmcnt(0)
	v_ashrrev_i32_e32 v97, 31, v96
	v_lshlrev_b64 v[98:99], 10, v[96:97]
	v_lshl_add_u64 v[98:99], v[98:99], 0, v[152:153]
	v_lshlrev_b64 v[98:99], 1, v[98:99]
	v_lshl_add_u64 v[108:109], s[16:17], 0, v[98:99]
	v_lshl_add_u64 v[104:105], s[36:37], 0, v[98:99]
	global_load_dwordx4 v[100:103], v[108:109], off
	s_nop 0
	global_load_dwordx4 v[104:107], v[104:105], off
	v_mul_f32_e32 v92, 0xbfb8aa3b, v92
	v_mul_f32_e32 v93, 0xbfb8aa3b, v93
	v_mul_f32_e32 v94, 0xbfb8aa3b, v94
	v_mul_f32_e32 v95, 0xbfb8aa3b, v95
	v_mul_f32_e32 v88, 0xbfb8aa3b, v88
	v_mul_f32_e32 v89, 0xbfb8aa3b, v89
	v_mul_f32_e32 v90, 0xbfb8aa3b, v90
	v_mul_f32_e32 v91, 0xbfb8aa3b, v91
	v_exp_f32_e32 v92, v92
	v_exp_f32_e32 v93, v93
	v_exp_f32_e32 v94, v94
	v_exp_f32_e32 v95, v95
	v_exp_f32_e32 v88, v88
	v_exp_f32_e32 v89, v89
	v_exp_f32_e32 v90, v90
	v_exp_f32_e32 v91, v91
	v_add_f32_e32 v92, 1.0, v92
	v_add_f32_e32 v93, 1.0, v93
	v_add_f32_e32 v94, 1.0, v94
	v_add_f32_e32 v95, 1.0, v95
	v_add_f32_e32 v88, 1.0, v88
	v_add_f32_e32 v89, 1.0, v89
	v_add_f32_e32 v90, 1.0, v90
	v_add_f32_e32 v91, 1.0, v91
	v_rcp_f32_e32 v92, v92
	v_rcp_f32_e32 v93, v93
	v_rcp_f32_e32 v94, v94
	v_rcp_f32_e32 v95, v95
	v_rcp_f32_e32 v88, v88
	v_rcp_f32_e32 v89, v89
	v_rcp_f32_e32 v90, v90
	v_rcp_f32_e32 v91, v91
	v_lshl_add_u64 v[110:111], s[12:13], 0, v[98:99]
	v_or_b32_e32 v98, 0x100, v98
	v_lshl_add_u64 v[112:113], s[16:17], 0, v[98:99]
	v_lshl_add_u64 v[114:115], s[36:37], 0, v[98:99]
	v_mul_f32_e32 v84, 0xbfb8aa3b, v84
	v_mul_f32_e32 v85, 0xbfb8aa3b, v85
	v_exp_f32_e32 v84, v84
	v_mul_f32_e32 v86, 0xbfb8aa3b, v86
	v_exp_f32_e32 v85, v85
	v_mul_f32_e32 v87, 0xbfb8aa3b, v87
	v_exp_f32_e32 v86, v86
	v_mul_f32_e32 v80, 0xbfb8aa3b, v80
	v_exp_f32_e32 v87, v87
	v_mul_f32_e32 v81, 0xbfb8aa3b, v81
	v_exp_f32_e32 v80, v80
	v_add_f32_e32 v84, 1.0, v84
	v_mul_f32_e32 v82, 0xbfb8aa3b, v82
	v_exp_f32_e32 v81, v81
	v_add_f32_e32 v85, 1.0, v85
	v_rcp_f32_e32 v84, v84
	v_mul_f32_e32 v83, 0xbfb8aa3b, v83
	v_exp_f32_e32 v82, v82
	v_add_f32_e32 v86, 1.0, v86
	v_rcp_f32_e32 v85, v85
	v_exp_f32_e32 v83, v83
	v_add_f32_e32 v87, 1.0, v87
	v_rcp_f32_e32 v86, v86
	v_add_f32_e32 v80, 1.0, v80
	v_rcp_f32_e32 v87, v87
	v_add_f32_e32 v81, 1.0, v81
	v_rcp_f32_e32 v80, v80
	v_add_f32_e32 v82, 1.0, v82
	v_rcp_f32_e32 v81, v81
	v_add_f32_e32 v83, 1.0, v83
	v_rcp_f32_e32 v82, v82
	v_rcp_f32_e32 v83, v83
	s_waitcnt vmcnt(1)
; __device__ __forceinline__ unsigned cvt_pk_bf16(float lo, float hi) { unsigned r; asm volatile("v_cvt_pk_bf16_f32 %0, %1, %2" : "=v"(r) : "v"(lo), "v"(hi)); return r; }
; __device__ __forceinline__ float bf_lo(unsigned w) { return __uint_as_float(w << 16); }
; __device__ __forceinline__ float bf_hi(unsigned w) { return __uint_as_float(w & 0xffff0000u); }
; __device__ __forceinline__ float sigmoid_f(float x) { return __builtin_amdgcn_rcpf(1.0f + __builtin_amdgcn_exp2f(-1.4426950408889634f * x)); }
;     __device__ __forceinline__ void operator()(const f32x4 (&acc)[2][2][4][2], const Unit& u, int wr, int wc, int fr, int fq) const {
;     ...
;             for (int m = 0; m < 4; ++m) { const int row = row0 + ai * HALF + m * 16; const size_t off = (size_t)row * 1024 + col0; float rs = 0.f;
; #pragma unroll
;                 for (int bj = 0; bj < 2; ++bj) { const size_t c = off + bj * HALF;
;                     const u32x4 hw = *(const u32x4*)(Hin + c); const u32x4 pw = *(const u32x4*)(PP + c);
;                     float o[8];
; #pragma unroll
;                     for (int n = 0; n < 2; ++n)
; #pragma unroll
;                         for (int w = 0; w < 2; ++w) { const unsigned hh = hw[2 * n + w], pp = pw[2 * n + w]; const f32x4 a = acc[ai][bj][m][n];
;                             o[4 * n + 2 * w] = bf_lo(hh) + bf_lo(pp) * sigmoid_f(a[2 * w]); o[4 * n + 2 * w + 1] = bf_hi(hh) + bf_hi(pp) * sigmoid_f(a[2 * w + 1]); }
;                     if (MODE == 1) { *(f32x4*)(Fout + c) = (f32x4){o[0], o[1], o[2], o[3]}; *(f32x4*)(Fout + c + 4) = (f32x4){o[4], o[5], o[6], o[7]}; }
;                     else { u32x4 w; w.x = cvt_pk_bf16(o[0], o[1]); w.y = cvt_pk_bf16(o[2], o[3]); w.z = cvt_pk_bf16(o[4], o[5]); w.w = cvt_pk_bf16(o[6], o[7]); *(u32x4*)(Hout + c) = w; }
;                     if (MODE == 2) {
; #pragma unroll
;                         for (int e = 0; e < 8; ++e) rs += o[e] * o[e];
;                         u32x4 w; w.x = cvt_pk_bf16(o[0] * gp[bj][0], o[1] * gp[bj][1]); w.y = cvt_pk_bf16(o[2] * gp[bj][2], o[3] * gp[bj][3]);
;                         w.z = cvt_pk_bf16(o[4] * gp[bj][4], o[5] * gp[bj][5]); w.w = cvt_pk_bf16(o[6] * gp[bj][6], o[7] * gp[bj][7]); *(u32x4*)(A2 + c) = w; } }
;                 if (MODE == 2) { rs += __shfl_xor(rs, 16); rs += __shfl_xor(rs, 32); if (fq == 0) atomicAdd(SS + row, rs); } }
	v_lshlrev_b32_e32 v116, 16, v100
	s_waitcnt vmcnt(0)
	v_lshlrev_b32_e32 v117, 16, v104
	v_and_b32_e32 v118, 0xffff0000, v100
	v_and_b32_e32 v100, 0xffff0000, v104
	v_lshlrev_b32_e32 v104, 16, v101
	v_lshlrev_b32_e32 v119, 16, v105
	v_and_b32_e32 v120, 0xffff0000, v101
	v_and_b32_e32 v101, 0xffff0000, v105
	v_lshlrev_b32_e32 v105, 16, v102
	v_lshlrev_b32_e32 v121, 16, v106
	v_and_b32_e32 v122, 0xffff0000, v102
	v_and_b32_e32 v102, 0xffff0000, v106
	v_lshlrev_b32_e32 v106, 16, v103
	v_lshlrev_b32_e32 v123, 16, v107
	v_and_b32_e32 v124, 0xffff0000, v103
	v_and_b32_e32 v103, 0xffff0000, v107
	v_fmac_f32_e32 v116, v92, v117
	v_fmac_f32_e32 v118, v93, v100
	v_fmac_f32_e32 v104, v94, v119
	v_fmac_f32_e32 v120, v95, v101
	v_fmac_f32_e32 v105, v88, v121
	v_fmac_f32_e32 v122, v89, v102
	v_fmac_f32_e32 v106, v90, v123
	v_fmac_f32_e32 v124, v91, v103
	v_cvt_pk_bf16_f32 v88, v116, v118
	v_cvt_pk_bf16_f32 v89, v104, v120
	v_cvt_pk_bf16_f32 v90, v105, v122
	v_cvt_pk_bf16_f32 v91, v106, v124
	v_mul_f32_e32 v92, v52, v116
	v_mul_f32_e32 v93, v53, v118
	v_mul_f32_e32 v94, v54, v104
	v_mul_f32_e32 v95, v55, v120
	v_mul_f32_e32 v100, v48, v105
	v_mul_f32_e32 v101, v49, v122
	v_mul_f32_e32 v102, v50, v106
	v_mul_f32_e32 v103, v51, v124
	global_store_dwordx4 v[108:109], v[88:91], off
	v_mul_f32_e32 v107, v118, v118
	v_fmac_f32_e32 v107, v116, v116
	v_cvt_pk_bf16_f32 v88, v92, v93
	v_cvt_pk_bf16_f32 v89, v94, v95
	v_cvt_pk_bf16_f32 v90, v100, v101
	v_cvt_pk_bf16_f32 v91, v102, v103
	global_load_dwordx4 v[92:95], v[112:113], off
	global_load_dwordx4 v[100:103], v[114:115], off
	v_fmac_f32_e32 v107, v104, v104
	v_fmac_f32_e32 v107, v120, v120
	v_fmac_f32_e32 v107, v105, v105
	v_fmac_f32_e32 v107, v122, v122
	global_store_dwordx4 v[110:111], v[88:91], off
	v_fmac_f32_e32 v107, v106, v106
	v_fmac_f32_e32 v107, v124, v124
	s_waitcnt vmcnt(2)
	v_lshlrev_b32_e32 v88, 16, v92
	s_waitcnt vmcnt(1)
	v_lshlrev_b32_e32 v89, 16, v100
	v_and_b32_e32 v90, 0xffff0000, v92
	v_and_b32_e32 v91, 0xffff0000, v100
	v_fmac_f32_e32 v88, v84, v89
	v_lshlrev_b32_e32 v92, 16, v93
	v_lshlrev_b32_e32 v100, 16, v101
	v_fmac_f32_e32 v90, v85, v91
	v_fmac_f32_e32 v107, v88, v88
	v_and_b32_e32 v93, 0xffff0000, v93
	v_and_b32_e32 v101, 0xffff0000, v101
	v_fmac_f32_e32 v92, v86, v100
	v_fmac_f32_e32 v107, v90, v90
	v_lshlrev_b32_e32 v104, 16, v94
	v_lshlrev_b32_e32 v105, 16, v102
	v_fmac_f32_e32 v93, v87, v101
	v_fmac_f32_e32 v107, v92, v92
	v_and_b32_e32 v94, 0xffff0000, v94
	v_and_b32_e32 v102, 0xffff0000, v102
	v_fmac_f32_e32 v104, v80, v105
	v_fmac_f32_e32 v107, v93, v93
	v_lshlrev_b32_e32 v106, 16, v95
	v_lshlrev_b32_e32 v108, 16, v103
	v_fmac_f32_e32 v94, v81, v102
	v_fmac_f32_e32 v107, v104, v104
	v_and_b32_e32 v95, 0xffff0000, v95
	v_and_b32_e32 v103, 0xffff0000, v103
	v_fmac_f32_e32 v106, v82, v108
	v_fmac_f32_e32 v107, v94, v94
	v_fmac_f32_e32 v95, v83, v103
	v_fmac_f32_e32 v107, v106, v106
	v_cvt_pk_bf16_f32 v80, v88, v90
	v_fmac_f32_e32 v107, v95, v95
	v_cvt_pk_bf16_f32 v81, v92, v93
	v_cvt_pk_bf16_f32 v82, v104, v94
	v_cvt_pk_bf16_f32 v83, v106, v95
	global_store_dwordx4 v[112:113], v[80:83], off
	ds_bpermute_b32 v80, v132, v107
	v_mul_f32_e32 v84, v44, v88
	v_mul_f32_e32 v85, v45, v90
	v_cvt_pk_bf16_f32 v82, v84, v85
	v_mul_f32_e32 v81, v36, v104
	v_mul_f32_e32 v84, v37, v94
	s_waitcnt lgkmcnt(0)
	v_add_f32_e32 v80, v107, v80
	v_mul_f32_e32 v86, v46, v92
	v_mul_f32_e32 v87, v47, v93
	v_cvt_pk_bf16_f32 v83, v86, v87
	v_cvt_pk_bf16_f32 v84, v81, v84
	ds_bpermute_b32 v81, v133, v80
	v_mul_f32_e32 v85, v38, v106
	v_mul_f32_e32 v86, v39, v95
	v_cvt_pk_bf16_f32 v85, v85, v86
	v_lshl_add_u64 v[86:87], s[12:13], 0, v[98:99]
	global_store_dwordx4 v[86:87], v[82:85], off
	s_and_saveexec_b64 s[54:55], s[4:5]
	s_cbranch_execz .LBB0_847
	v_lshl_add_u64 v[82:83], v[96:97], 2, s[18:19]
	s_waitcnt lgkmcnt(0)
	v_add_f32_e32 v80, v80, v81
	v_mov_b32_e32 v233, v80
.LBB0_847:
	s_or_b64 exec, exec, s[54:55]
	v_add_u32_e32 v80, 0x80, v154
	s_waitcnt lgkmcnt(0)
	v_ashrrev_i32_e32 v81, 31, v80
	v_lshlrev_b64 v[82:83], 10, v[80:81]
	v_lshl_add_u64 v[82:83], v[82:83], 0, v[152:153]
	v_lshlrev_b64 v[82:83], 1, v[82:83]
	v_lshl_add_u64 v[92:93], s[16:17], 0, v[82:83]
	v_lshl_add_u64 v[88:89], s[36:37], 0, v[82:83]
	global_load_dwordx4 v[84:87], v[92:93], off
	s_nop 0
	global_load_dwordx4 v[88:91], v[88:89], off
	v_mul_f32_e32 v76, 0xbfb8aa3b, v76
	v_mul_f32_e32 v77, 0xbfb8aa3b, v77
	v_mul_f32_e32 v78, 0xbfb8aa3b, v78
	v_mul_f32_e32 v79, 0xbfb8aa3b, v79
	v_mul_f32_e32 v72, 0xbfb8aa3b, v72
	v_mul_f32_e32 v73, 0xbfb8aa3b, v73
	v_mul_f32_e32 v74, 0xbfb8aa3b, v74
	v_mul_f32_e32 v75, 0xbfb8aa3b, v75
	v_exp_f32_e32 v76, v76
	v_exp_f32_e32 v77, v77
	v_exp_f32_e32 v78, v78
	v_exp_f32_e32 v79, v79
	v_exp_f32_e32 v72, v72
	v_exp_f32_e32 v73, v73
	v_exp_f32_e32 v74, v74
	v_exp_f32_e32 v75, v75
	v_add_f32_e32 v76, 1.0, v76
	v_add_f32_e32 v77, 1.0, v77
	v_add_f32_e32 v78, 1.0, v78
	v_add_f32_e32 v79, 1.0, v79
	v_add_f32_e32 v72, 1.0, v72
	v_add_f32_e32 v73, 1.0, v73
	v_add_f32_e32 v74, 1.0, v74
	v_add_f32_e32 v75, 1.0, v75
	v_rcp_f32_e32 v76, v76
	v_rcp_f32_e32 v77, v77
	v_rcp_f32_e32 v78, v78
	v_rcp_f32_e32 v79, v79
	v_rcp_f32_e32 v72, v72
	v_rcp_f32_e32 v73, v73
	v_rcp_f32_e32 v74, v74
	v_rcp_f32_e32 v75, v75
	v_lshl_add_u64 v[94:95], s[12:13], 0, v[82:83]
	v_or_b32_e32 v82, 0x100, v82
	v_lshl_add_u64 v[96:97], s[16:17], 0, v[82:83]
	v_lshl_add_u64 v[98:99], s[36:37], 0, v[82:83]
	v_mul_f32_e32 v68, 0xbfb8aa3b, v68
	v_mul_f32_e32 v69, 0xbfb8aa3b, v69
	v_exp_f32_e32 v68, v68
	v_mul_f32_e32 v70, 0xbfb8aa3b, v70
	v_exp_f32_e32 v69, v69
	v_mul_f32_e32 v71, 0xbfb8aa3b, v71
	v_exp_f32_e32 v70, v70
	v_mul_f32_e32 v64, 0xbfb8aa3b, v64
	v_exp_f32_e32 v71, v71
	v_mul_f32_e32 v65, 0xbfb8aa3b, v65
	v_exp_f32_e32 v64, v64
	v_add_f32_e32 v68, 1.0, v68
	v_mul_f32_e32 v66, 0xbfb8aa3b, v66
	v_exp_f32_e32 v65, v65
	v_add_f32_e32 v69, 1.0, v69
	v_rcp_f32_e32 v68, v68
	v_mul_f32_e32 v67, 0xbfb8aa3b, v67
	v_exp_f32_e32 v66, v66
	v_add_f32_e32 v70, 1.0, v70
	v_rcp_f32_e32 v69, v69
	v_exp_f32_e32 v67, v67
	v_add_f32_e32 v71, 1.0, v71
	v_rcp_f32_e32 v70, v70
	v_add_f32_e32 v64, 1.0, v64
	v_rcp_f32_e32 v71, v71
	v_add_f32_e32 v65, 1.0, v65
	v_rcp_f32_e32 v64, v64
	v_add_f32_e32 v66, 1.0, v66
	v_rcp_f32_e32 v65, v65
	v_add_f32_e32 v67, 1.0, v67
	v_rcp_f32_e32 v66, v66
	v_rcp_f32_e32 v67, v67
	s_waitcnt vmcnt(1)
; __device__ __forceinline__ unsigned cvt_pk_bf16(float lo, float hi) { unsigned r; asm volatile("v_cvt_pk_bf16_f32 %0, %1, %2" : "=v"(r) : "v"(lo), "v"(hi)); return r; }
; __device__ __forceinline__ float bf_lo(unsigned w) { return __uint_as_float(w << 16); }
; __device__ __forceinline__ float bf_hi(unsigned w) { return __uint_as_float(w & 0xffff0000u); }
; __device__ __forceinline__ float sigmoid_f(float x) { return __builtin_amdgcn_rcpf(1.0f + __builtin_amdgcn_exp2f(-1.4426950408889634f * x)); }
;     __device__ __forceinline__ void operator()(const f32x4 (&acc)[2][2][4][2], const Unit& u, int wr, int wc, int fr, int fq) const {
;     ...
;             for (int m = 0; m < 4; ++m) { const int row = row0 + ai * HALF + m * 16; const size_t off = (size_t)row * 1024 + col0; float rs = 0.f;
; #pragma unroll
;                 for (int bj = 0; bj < 2; ++bj) { const size_t c = off + bj * HALF;
;                     const u32x4 hw = *(const u32x4*)(Hin + c); const u32x4 pw = *(const u32x4*)(PP + c);
;                     float o[8];
; #pragma unroll
;                     for (int n = 0; n < 2; ++n)
; #pragma unroll
;                         for (int w = 0; w < 2; ++w) { const unsigned hh = hw[2 * n + w], pp = pw[2 * n + w]; const f32x4 a = acc[ai][bj][m][n];
;                             o[4 * n + 2 * w] = bf_lo(hh) + bf_lo(pp) * sigmoid_f(a[2 * w]); o[4 * n + 2 * w + 1] = bf_hi(hh) + bf_hi(pp) * sigmoid_f(a[2 * w + 1]); }
;                     if (MODE == 1) { *(f32x4*)(Fout + c) = (f32x4){o[0], o[1], o[2], o[3]}; *(f32x4*)(Fout + c + 4) = (f32x4){o[4], o[5], o[6], o[7]}; }
;                     else { u32x4 w; w.x = cvt_pk_bf16(o[0], o[1]); w.y = cvt_pk_bf16(o[2], o[3]); w.z = cvt_pk_bf16(o[4], o[5]); w.w = cvt_pk_bf16(o[6], o[7]); *(u32x4*)(Hout + c) = w; }
;                     if (MODE == 2) {
; #pragma unroll
;                         for (int e = 0; e < 8; ++e) rs += o[e] * o[e];
;                         u32x4 w; w.x = cvt_pk_bf16(o[0] * gp[bj][0], o[1] * gp[bj][1]); w.y = cvt_pk_bf16(o[2] * gp[bj][2], o[3] * gp[bj][3]);
;                         w.z = cvt_pk_bf16(o[4] * gp[bj][4], o[5] * gp[bj][5]); w.w = cvt_pk_bf16(o[6] * gp[bj][6], o[7] * gp[bj][7]); *(u32x4*)(A2 + c) = w; } }
;                 if (MODE == 2) { rs += __shfl_xor(rs, 16); rs += __shfl_xor(rs, 32); if (fq == 0) atomicAdd(SS + row, rs); } }
	v_lshlrev_b32_e32 v100, 16, v84
	s_waitcnt vmcnt(0)
	v_lshlrev_b32_e32 v101, 16, v88
	v_and_b32_e32 v102, 0xffff0000, v84
	v_and_b32_e32 v84, 0xffff0000, v88
	v_lshlrev_b32_e32 v88, 16, v85
	v_lshlrev_b32_e32 v103, 16, v89
	v_and_b32_e32 v104, 0xffff0000, v85
	v_and_b32_e32 v85, 0xffff0000, v89
	v_lshlrev_b32_e32 v89, 16, v86
	v_lshlrev_b32_e32 v105, 16, v90
	v_and_b32_e32 v106, 0xffff0000, v86
	v_and_b32_e32 v86, 0xffff0000, v90
	v_lshlrev_b32_e32 v90, 16, v87
	v_lshlrev_b32_e32 v107, 16, v91
	v_and_b32_e32 v108, 0xffff0000, v87
	v_and_b32_e32 v87, 0xffff0000, v91
	v_fmac_f32_e32 v100, v76, v101
	v_fmac_f32_e32 v102, v77, v84
	v_fmac_f32_e32 v88, v78, v103
	v_fmac_f32_e32 v104, v79, v85
	v_fmac_f32_e32 v89, v72, v105
	v_fmac_f32_e32 v106, v73, v86
	v_fmac_f32_e32 v90, v74, v107
	v_fmac_f32_e32 v108, v75, v87
	v_cvt_pk_bf16_f32 v72, v100, v102
	v_cvt_pk_bf16_f32 v73, v88, v104
	v_cvt_pk_bf16_f32 v74, v89, v106
	v_cvt_pk_bf16_f32 v75, v90, v108
	v_mul_f32_e32 v76, v52, v100
	v_mul_f32_e32 v77, v53, v102
	v_mul_f32_e32 v78, v54, v88
	v_mul_f32_e32 v79, v55, v104
	v_mul_f32_e32 v84, v48, v89
	v_mul_f32_e32 v85, v49, v106
	v_mul_f32_e32 v86, v50, v90
	v_mul_f32_e32 v87, v51, v108
	global_store_dwordx4 v[92:93], v[72:75], off
	v_mul_f32_e32 v91, v102, v102
	v_fmac_f32_e32 v91, v100, v100
	v_cvt_pk_bf16_f32 v72, v76, v77
	v_cvt_pk_bf16_f32 v73, v78, v79
	v_cvt_pk_bf16_f32 v74, v84, v85
	v_cvt_pk_bf16_f32 v75, v86, v87
	global_load_dwordx4 v[76:79], v[96:97], off
	global_load_dwordx4 v[84:87], v[98:99], off
	v_fmac_f32_e32 v91, v88, v88
	v_fmac_f32_e32 v91, v104, v104
	v_fmac_f32_e32 v91, v89, v89
	v_fmac_f32_e32 v91, v106, v106
	global_store_dwordx4 v[94:95], v[72:75], off
	v_fmac_f32_e32 v91, v90, v90
	v_fmac_f32_e32 v91, v108, v108
	s_waitcnt vmcnt(2)
	v_lshlrev_b32_e32 v72, 16, v76
	s_waitcnt vmcnt(1)
	v_lshlrev_b32_e32 v73, 16, v84
	v_and_b32_e32 v74, 0xffff0000, v76
	v_and_b32_e32 v75, 0xffff0000, v84
	v_fmac_f32_e32 v72, v68, v73
	v_lshlrev_b32_e32 v76, 16, v77
	v_lshlrev_b32_e32 v84, 16, v85
	v_fmac_f32_e32 v74, v69, v75
	v_fmac_f32_e32 v91, v72, v72
	v_and_b32_e32 v77, 0xffff0000, v77
	v_and_b32_e32 v85, 0xffff0000, v85
	v_fmac_f32_e32 v76, v70, v84
	v_fmac_f32_e32 v91, v74, v74
	v_lshlrev_b32_e32 v88, 16, v78
	v_lshlrev_b32_e32 v89, 16, v86
	v_fmac_f32_e32 v77, v71, v85
	v_fmac_f32_e32 v91, v76, v76
	v_and_b32_e32 v78, 0xffff0000, v78
	v_and_b32_e32 v86, 0xffff0000, v86
	v_fmac_f32_e32 v88, v64, v89
	v_fmac_f32_e32 v91, v77, v77
	v_lshlrev_b32_e32 v90, 16, v79
	v_lshlrev_b32_e32 v92, 16, v87
	v_fmac_f32_e32 v78, v65, v86
	v_fmac_f32_e32 v91, v88, v88
	v_and_b32_e32 v79, 0xffff0000, v79
	v_and_b32_e32 v87, 0xffff0000, v87
	v_fmac_f32_e32 v90, v66, v92
	v_fmac_f32_e32 v91, v78, v78
	v_fmac_f32_e32 v79, v67, v87
	v_fmac_f32_e32 v91, v90, v90
	v_cvt_pk_bf16_f32 v64, v72, v74
	v_fmac_f32_e32 v91, v79, v79
	v_cvt_pk_bf16_f32 v65, v76, v77
	v_cvt_pk_bf16_f32 v66, v88, v78
	v_cvt_pk_bf16_f32 v67, v90, v79
	global_store_dwordx4 v[96:97], v[64:67], off
	ds_bpermute_b32 v64, v132, v91
	v_mul_f32_e32 v68, v44, v72
	v_mul_f32_e32 v69, v45, v74
	v_cvt_pk_bf16_f32 v66, v68, v69
	v_mul_f32_e32 v65, v36, v88
	v_mul_f32_e32 v68, v37, v78
	s_waitcnt lgkmcnt(0)
	v_add_f32_e32 v64, v91, v64
	v_mul_f32_e32 v70, v46, v76
	v_mul_f32_e32 v71, v47, v77
	v_cvt_pk_bf16_f32 v67, v70, v71
	v_cvt_pk_bf16_f32 v68, v65, v68
	ds_bpermute_b32 v65, v133, v64
	v_mul_f32_e32 v69, v38, v90
	v_mul_f32_e32 v70, v39, v79
	v_cvt_pk_bf16_f32 v69, v69, v70
	v_lshl_add_u64 v[70:71], s[12:13], 0, v[82:83]
	global_store_dwordx4 v[70:71], v[66:69], off
	s_and_saveexec_b64 s[54:55], s[4:5]
	s_cbranch_execz .LBB0_849
	v_lshl_add_u64 v[66:67], v[80:81], 2, s[18:19]
	s_waitcnt lgkmcnt(0)
	v_add_f32_e32 v64, v64, v65
	v_mov_b32_e32 v234, v64
.LBB0_849:
	s_or_b64 exec, exec, s[54:55]
	v_add_u32_e32 v64, 0x90, v154
	s_waitcnt lgkmcnt(0)
	v_ashrrev_i32_e32 v65, 31, v64
	v_lshlrev_b64 v[66:67], 10, v[64:65]
	v_lshl_add_u64 v[66:67], v[66:67], 0, v[152:153]
	v_lshlrev_b64 v[66:67], 1, v[66:67]
	v_lshl_add_u64 v[76:77], s[16:17], 0, v[66:67]
	v_lshl_add_u64 v[72:73], s[36:37], 0, v[66:67]
	global_load_dwordx4 v[68:71], v[76:77], off
	s_nop 0
	global_load_dwordx4 v[72:75], v[72:73], off
	v_mul_f32_e32 v60, 0xbfb8aa3b, v60
	v_mul_f32_e32 v61, 0xbfb8aa3b, v61
	v_mul_f32_e32 v62, 0xbfb8aa3b, v62
	v_mul_f32_e32 v63, 0xbfb8aa3b, v63
	v_mul_f32_e32 v56, 0xbfb8aa3b, v56
	v_mul_f32_e32 v57, 0xbfb8aa3b, v57
	v_mul_f32_e32 v58, 0xbfb8aa3b, v58
	v_mul_f32_e32 v59, 0xbfb8aa3b, v59
	v_exp_f32_e32 v60, v60
	v_exp_f32_e32 v61, v61
	v_exp_f32_e32 v62, v62
	v_exp_f32_e32 v63, v63
	v_exp_f32_e32 v56, v56
	v_exp_f32_e32 v57, v57
	v_exp_f32_e32 v58, v58
	v_exp_f32_e32 v59, v59
	v_add_f32_e32 v60, 1.0, v60
	v_add_f32_e32 v61, 1.0, v61
	v_add_f32_e32 v62, 1.0, v62
	v_add_f32_e32 v63, 1.0, v63
	v_add_f32_e32 v56, 1.0, v56
	v_add_f32_e32 v57, 1.0, v57
	v_add_f32_e32 v58, 1.0, v58
	v_add_f32_e32 v59, 1.0, v59
	v_rcp_f32_e32 v60, v60
	v_rcp_f32_e32 v61, v61
	v_rcp_f32_e32 v62, v62
	v_rcp_f32_e32 v63, v63
	v_rcp_f32_e32 v56, v56
	v_rcp_f32_e32 v57, v57
	v_rcp_f32_e32 v58, v58
	v_rcp_f32_e32 v59, v59
	v_lshl_add_u64 v[78:79], s[12:13], 0, v[66:67]
	v_or_b32_e32 v66, 0x100, v66
	v_lshl_add_u64 v[80:81], s[16:17], 0, v[66:67]
	v_lshl_add_u64 v[82:83], s[36:37], 0, v[66:67]
	v_mul_f32_e32 v40, 0xbfb8aa3b, v40
	v_mul_f32_e32 v41, 0xbfb8aa3b, v41
	v_exp_f32_e32 v40, v40
	v_mul_f32_e32 v42, 0xbfb8aa3b, v42
	v_exp_f32_e32 v41, v41
	v_mul_f32_e32 v43, 0xbfb8aa3b, v43
	v_exp_f32_e32 v42, v42
	v_mul_f32_e32 v32, 0xbfb8aa3b, v32
	v_exp_f32_e32 v43, v43
	v_mul_f32_e32 v33, 0xbfb8aa3b, v33
	v_exp_f32_e32 v32, v32
	v_add_f32_e32 v40, 1.0, v40
	v_mul_f32_e32 v34, 0xbfb8aa3b, v34
	v_exp_f32_e32 v33, v33
	v_add_f32_e32 v41, 1.0, v41
	v_rcp_f32_e32 v40, v40
	v_mul_f32_e32 v35, 0xbfb8aa3b, v35
	v_exp_f32_e32 v34, v34
	v_add_f32_e32 v42, 1.0, v42
	v_rcp_f32_e32 v41, v41
	v_exp_f32_e32 v35, v35
	v_add_f32_e32 v43, 1.0, v43
	v_rcp_f32_e32 v42, v42
	v_add_f32_e32 v32, 1.0, v32
	v_rcp_f32_e32 v43, v43
	v_add_f32_e32 v33, 1.0, v33
	v_rcp_f32_e32 v32, v32
	v_add_f32_e32 v34, 1.0, v34
	v_rcp_f32_e32 v33, v33
	v_add_f32_e32 v35, 1.0, v35
	v_rcp_f32_e32 v34, v34
	v_rcp_f32_e32 v35, v35
	s_waitcnt vmcnt(1)
; __device__ __forceinline__ unsigned cvt_pk_bf16(float lo, float hi) { unsigned r; asm volatile("v_cvt_pk_bf16_f32 %0, %1, %2" : "=v"(r) : "v"(lo), "v"(hi)); return r; }
; __device__ __forceinline__ float bf_lo(unsigned w) { return __uint_as_float(w << 16); }
; __device__ __forceinline__ float bf_hi(unsigned w) { return __uint_as_float(w & 0xffff0000u); }
; __device__ __forceinline__ float sigmoid_f(float x) { return __builtin_amdgcn_rcpf(1.0f + __builtin_amdgcn_exp2f(-1.4426950408889634f * x)); }
;     __device__ __forceinline__ void operator()(const f32x4 (&acc)[2][2][4][2], const Unit& u, int wr, int wc, int fr, int fq) const {
;     ...
;                 for (int bj = 0; bj < 2; ++bj) { const size_t c = off + bj * HALF;
;                     const u32x4 hw = *(const u32x4*)(Hin + c); const u32x4 pw = *(const u32x4*)(PP + c);
;                     float o[8];
; #pragma unroll
;                     for (int n = 0; n < 2; ++n)
; #pragma unroll
;                         for (int w = 0; w < 2; ++w) { const unsigned hh = hw[2 * n + w], pp = pw[2 * n + w]; const f32x4 a = acc[ai][bj][m][n];
;                             o[4 * n + 2 * w] = bf_lo(hh) + bf_lo(pp) * sigmoid_f(a[2 * w]); o[4 * n + 2 * w + 1] = bf_hi(hh) + bf_hi(pp) * sigmoid_f(a[2 * w + 1]); }
;                     if (MODE == 1) { *(f32x4*)(Fout + c) = (f32x4){o[0], o[1], o[2], o[3]}; *(f32x4*)(Fout + c + 4) = (f32x4){o[4], o[5], o[6], o[7]}; }
;                     else { u32x4 w; w.x = cvt_pk_bf16(o[0], o[1]); w.y = cvt_pk_bf16(o[2], o[3]); w.z = cvt_pk_bf16(o[4], o[5]); w.w = cvt_pk_bf16(o[6], o[7]); *(u32x4*)(Hout + c) = w; }
;                     if (MODE == 2) {
; #pragma unroll
;                         for (int e = 0; e < 8; ++e) rs += o[e] * o[e];
;                         u32x4 w; w.x = cvt_pk_bf16(o[0] * gp[bj][0], o[1] * gp[bj][1]); w.y = cvt_pk_bf16(o[2] * gp[bj][2], o[3] * gp[bj][3]);
;                         w.z = cvt_pk_bf16(o[4] * gp[bj][4], o[5] * gp[bj][5]); w.w = cvt_pk_bf16(o[6] * gp[bj][6], o[7] * gp[bj][7]); *(u32x4*)(A2 + c) = w; } }
;                 if (MODE == 2) { rs += __shfl_xor(rs, 16); rs += __shfl_xor(rs, 32); if (fq == 0) atomicAdd(SS + row, rs); } }
	v_lshlrev_b32_e32 v84, 16, v68
	s_waitcnt vmcnt(0)
	v_lshlrev_b32_e32 v85, 16, v72
	v_and_b32_e32 v86, 0xffff0000, v68
	v_and_b32_e32 v68, 0xffff0000, v72
	v_lshlrev_b32_e32 v72, 16, v69
	v_lshlrev_b32_e32 v87, 16, v73
	v_and_b32_e32 v88, 0xffff0000, v69
	v_and_b32_e32 v69, 0xffff0000, v73
	v_lshlrev_b32_e32 v73, 16, v70
	v_lshlrev_b32_e32 v89, 16, v74
	v_and_b32_e32 v90, 0xffff0000, v70
	v_and_b32_e32 v70, 0xffff0000, v74
	v_lshlrev_b32_e32 v74, 16, v71
	v_lshlrev_b32_e32 v91, 16, v75
	v_and_b32_e32 v92, 0xffff0000, v71
	v_and_b32_e32 v71, 0xffff0000, v75
	v_fmac_f32_e32 v84, v60, v85
	v_fmac_f32_e32 v86, v61, v68
	v_fmac_f32_e32 v72, v62, v87
	v_fmac_f32_e32 v88, v63, v69
	v_fmac_f32_e32 v73, v56, v89
	v_fmac_f32_e32 v90, v57, v70
	v_fmac_f32_e32 v74, v58, v91
	v_fmac_f32_e32 v92, v59, v71
	v_cvt_pk_bf16_f32 v56, v84, v86
	v_cvt_pk_bf16_f32 v57, v72, v88
	v_cvt_pk_bf16_f32 v58, v73, v90
	v_cvt_pk_bf16_f32 v59, v74, v92
	v_mul_f32_e32 v60, v52, v84
	v_mul_f32_e32 v61, v53, v86
	v_mul_f32_e32 v62, v54, v72
	v_mul_f32_e32 v63, v55, v88
	v_mul_f32_e32 v68, v48, v73
	v_mul_f32_e32 v69, v49, v90
	v_mul_f32_e32 v70, v50, v74
	v_mul_f32_e32 v71, v51, v92
	global_store_dwordx4 v[76:77], v[56:59], off
	v_mul_f32_e32 v75, v86, v86
	v_fmac_f32_e32 v75, v84, v84
	v_cvt_pk_bf16_f32 v56, v60, v61
	v_cvt_pk_bf16_f32 v57, v62, v63
	v_cvt_pk_bf16_f32 v58, v68, v69
	v_cvt_pk_bf16_f32 v59, v70, v71
	global_load_dwordx4 v[60:63], v[80:81], off
	global_load_dwordx4 v[68:71], v[82:83], off
	v_fmac_f32_e32 v75, v72, v72
	v_fmac_f32_e32 v75, v88, v88
	v_fmac_f32_e32 v75, v73, v73
	v_fmac_f32_e32 v75, v90, v90
	global_store_dwordx4 v[78:79], v[56:59], off
	v_fmac_f32_e32 v75, v74, v74
	v_fmac_f32_e32 v75, v92, v92
	s_waitcnt vmcnt(2)
	v_lshlrev_b32_e32 v56, 16, v60
	s_waitcnt vmcnt(1)
	v_lshlrev_b32_e32 v57, 16, v68
	v_and_b32_e32 v58, 0xffff0000, v60
	v_and_b32_e32 v59, 0xffff0000, v68
	v_fmac_f32_e32 v56, v40, v57
	v_lshlrev_b32_e32 v60, 16, v61
	v_lshlrev_b32_e32 v68, 16, v69
	v_fmac_f32_e32 v58, v41, v59
	v_fmac_f32_e32 v75, v56, v56
	v_and_b32_e32 v61, 0xffff0000, v61
	v_and_b32_e32 v69, 0xffff0000, v69
	v_fmac_f32_e32 v60, v42, v68
	v_fmac_f32_e32 v75, v58, v58
	v_lshlrev_b32_e32 v72, 16, v62
	v_lshlrev_b32_e32 v73, 16, v70
	v_fmac_f32_e32 v61, v43, v69
	v_fmac_f32_e32 v75, v60, v60
	v_and_b32_e32 v62, 0xffff0000, v62
	v_and_b32_e32 v70, 0xffff0000, v70
	v_fmac_f32_e32 v72, v32, v73
	v_fmac_f32_e32 v75, v61, v61
	v_lshlrev_b32_e32 v74, 16, v63
	v_lshlrev_b32_e32 v76, 16, v71
	v_fmac_f32_e32 v62, v33, v70
	v_fmac_f32_e32 v75, v72, v72
	v_and_b32_e32 v63, 0xffff0000, v63
	v_and_b32_e32 v71, 0xffff0000, v71
	v_fmac_f32_e32 v74, v34, v76
	v_fmac_f32_e32 v75, v62, v62
	v_fmac_f32_e32 v63, v35, v71
	v_fmac_f32_e32 v75, v74, v74
	v_cvt_pk_bf16_f32 v32, v56, v58
	v_fmac_f32_e32 v75, v63, v63
	v_cvt_pk_bf16_f32 v33, v60, v61
	v_cvt_pk_bf16_f32 v34, v72, v62
	v_cvt_pk_bf16_f32 v35, v74, v63
	global_store_dwordx4 v[80:81], v[32:35], off
	ds_bpermute_b32 v32, v132, v75
	v_mul_f32_e32 v40, v44, v56
	v_mul_f32_e32 v41, v45, v58
	v_mul_f32_e32 v42, v46, v60
	v_mul_f32_e32 v33, v36, v72
	s_waitcnt lgkmcnt(0)
	v_add_f32_e32 v32, v75, v32
	v_mul_f32_e32 v43, v47, v61
	v_cvt_pk_bf16_f32 v40, v40, v41
	v_cvt_pk_bf16_f32 v41, v42, v43
	v_mul_f32_e32 v34, v37, v62
	v_cvt_pk_bf16_f32 v42, v33, v34
	ds_bpermute_b32 v33, v133, v32
	v_mul_f32_e32 v34, v38, v74
	v_mul_f32_e32 v35, v39, v63
	v_cvt_pk_bf16_f32 v43, v34, v35
	v_lshl_add_u64 v[34:35], s[12:13], 0, v[66:67]
	global_store_dwordx4 v[34:35], v[40:43], off
	s_and_saveexec_b64 s[54:55], s[4:5]
	s_cbranch_execz .LBB0_851
	v_lshl_add_u64 v[34:35], v[64:65], 2, s[18:19]
	s_waitcnt lgkmcnt(0)
	v_add_f32_e32 v32, v32, v33
	v_mov_b32_e32 v235, v32
.LBB0_851:
	s_or_b64 exec, exec, s[54:55]
	v_add_u32_e32 v32, 0xa0, v154
	s_waitcnt lgkmcnt(0)
	v_ashrrev_i32_e32 v33, 31, v32
	v_lshlrev_b64 v[34:35], 10, v[32:33]
	v_lshl_add_u64 v[34:35], v[34:35], 0, v[152:153]
	v_lshlrev_b64 v[34:35], 1, v[34:35]
	v_lshl_add_u64 v[60:61], s[16:17], 0, v[34:35]
	v_lshl_add_u64 v[56:57], s[36:37], 0, v[34:35]
	global_load_dwordx4 v[40:43], v[60:61], off
	s_nop 0
	global_load_dwordx4 v[56:59], v[56:57], off
	v_mul_f32_e32 v28, 0xbfb8aa3b, v28
	v_mul_f32_e32 v29, 0xbfb8aa3b, v29
	v_mul_f32_e32 v30, 0xbfb8aa3b, v30
	v_mul_f32_e32 v31, 0xbfb8aa3b, v31
	v_mul_f32_e32 v24, 0xbfb8aa3b, v24
	v_mul_f32_e32 v25, 0xbfb8aa3b, v25
	v_mul_f32_e32 v26, 0xbfb8aa3b, v26
	v_mul_f32_e32 v27, 0xbfb8aa3b, v27
	v_exp_f32_e32 v28, v28
	v_exp_f32_e32 v29, v29
	v_exp_f32_e32 v30, v30
	v_exp_f32_e32 v31, v31
	v_exp_f32_e32 v24, v24
	v_exp_f32_e32 v25, v25
	v_exp_f32_e32 v26, v26
	v_exp_f32_e32 v27, v27
	v_add_f32_e32 v28, 1.0, v28
	v_add_f32_e32 v29, 1.0, v29
	v_add_f32_e32 v30, 1.0, v30
	v_add_f32_e32 v31, 1.0, v31
	v_add_f32_e32 v24, 1.0, v24
	v_add_f32_e32 v25, 1.0, v25
	v_add_f32_e32 v26, 1.0, v26
	v_add_f32_e32 v27, 1.0, v27
	v_rcp_f32_e32 v28, v28
	v_rcp_f32_e32 v29, v29
	v_rcp_f32_e32 v30, v30
	v_rcp_f32_e32 v31, v31
	v_rcp_f32_e32 v24, v24
	v_rcp_f32_e32 v25, v25
	v_rcp_f32_e32 v26, v26
	v_rcp_f32_e32 v27, v27
	v_lshl_add_u64 v[62:63], s[12:13], 0, v[34:35]
	v_or_b32_e32 v34, 0x100, v34
	v_lshl_add_u64 v[64:65], s[16:17], 0, v[34:35]
	v_lshl_add_u64 v[66:67], s[36:37], 0, v[34:35]
	v_mul_f32_e32 v20, 0xbfb8aa3b, v20
	v_mul_f32_e32 v21, 0xbfb8aa3b, v21
	v_exp_f32_e32 v20, v20
	v_mul_f32_e32 v22, 0xbfb8aa3b, v22
	v_exp_f32_e32 v21, v21
	v_mul_f32_e32 v23, 0xbfb8aa3b, v23
	v_exp_f32_e32 v22, v22
	v_mul_f32_e32 v16, 0xbfb8aa3b, v16
	v_exp_f32_e32 v23, v23
	v_mul_f32_e32 v17, 0xbfb8aa3b, v17
	v_exp_f32_e32 v16, v16
	v_add_f32_e32 v20, 1.0, v20
	v_mul_f32_e32 v18, 0xbfb8aa3b, v18
	v_exp_f32_e32 v17, v17
	v_add_f32_e32 v21, 1.0, v21
	v_rcp_f32_e32 v20, v20
	v_mul_f32_e32 v19, 0xbfb8aa3b, v19
	v_exp_f32_e32 v18, v18
	v_add_f32_e32 v22, 1.0, v22
	v_rcp_f32_e32 v21, v21
	v_exp_f32_e32 v19, v19
	v_add_f32_e32 v23, 1.0, v23
	v_rcp_f32_e32 v22, v22
	v_add_f32_e32 v16, 1.0, v16
	v_rcp_f32_e32 v23, v23
	v_add_f32_e32 v17, 1.0, v17
	v_rcp_f32_e32 v16, v16
	v_add_f32_e32 v18, 1.0, v18
	v_rcp_f32_e32 v17, v17
	v_add_f32_e32 v19, 1.0, v19
	v_rcp_f32_e32 v18, v18
	v_rcp_f32_e32 v19, v19
	s_waitcnt vmcnt(1)
; __device__ __forceinline__ unsigned cvt_pk_bf16(float lo, float hi) { unsigned r; asm volatile("v_cvt_pk_bf16_f32 %0, %1, %2" : "=v"(r) : "v"(lo), "v"(hi)); return r; }
; __device__ __forceinline__ float bf_lo(unsigned w) { return __uint_as_float(w << 16); }
; __device__ __forceinline__ float bf_hi(unsigned w) { return __uint_as_float(w & 0xffff0000u); }
; __device__ __forceinline__ float sigmoid_f(float x) { return __builtin_amdgcn_rcpf(1.0f + __builtin_amdgcn_exp2f(-1.4426950408889634f * x)); }
;     __device__ __forceinline__ void operator()(const f32x4 (&acc)[2][2][4][2], const Unit& u, int wr, int wc, int fr, int fq) const {
;     ...
;                 for (int bj = 0; bj < 2; ++bj) { const size_t c = off + bj * HALF;
;                     const u32x4 hw = *(const u32x4*)(Hin + c); const u32x4 pw = *(const u32x4*)(PP + c);
;                     float o[8];
; #pragma unroll
;                     for (int n = 0; n < 2; ++n)
; #pragma unroll
;                         for (int w = 0; w < 2; ++w) { const unsigned hh = hw[2 * n + w], pp = pw[2 * n + w]; const f32x4 a = acc[ai][bj][m][n];
;                             o[4 * n + 2 * w] = bf_lo(hh) + bf_lo(pp) * sigmoid_f(a[2 * w]); o[4 * n + 2 * w + 1] = bf_hi(hh) + bf_hi(pp) * sigmoid_f(a[2 * w + 1]); }
;                     if (MODE == 1) { *(f32x4*)(Fout + c) = (f32x4){o[0], o[1], o[2], o[3]}; *(f32x4*)(Fout + c + 4) = (f32x4){o[4], o[5], o[6], o[7]}; }
;                     else { u32x4 w; w.x = cvt_pk_bf16(o[0], o[1]); w.y = cvt_pk_bf16(o[2], o[3]); w.z = cvt_pk_bf16(o[4], o[5]); w.w = cvt_pk_bf16(o[6], o[7]); *(u32x4*)(Hout + c) = w; }
;                     if (MODE == 2) {
; #pragma unroll
;                         for (int e = 0; e < 8; ++e) rs += o[e] * o[e];
;                         u32x4 w; w.x = cvt_pk_bf16(o[0] * gp[bj][0], o[1] * gp[bj][1]); w.y = cvt_pk_bf16(o[2] * gp[bj][2], o[3] * gp[bj][3]);
;                         w.z = cvt_pk_bf16(o[4] * gp[bj][4], o[5] * gp[bj][5]); w.w = cvt_pk_bf16(o[6] * gp[bj][6], o[7] * gp[bj][7]); *(u32x4*)(A2 + c) = w; } }
;                 if (MODE == 2) { rs += __shfl_xor(rs, 16); rs += __shfl_xor(rs, 32); if (fq == 0) atomicAdd(SS + row, rs); } }
	v_lshlrev_b32_e32 v68, 16, v40
	s_waitcnt vmcnt(0)
	v_lshlrev_b32_e32 v69, 16, v56
	v_and_b32_e32 v70, 0xffff0000, v40
	v_and_b32_e32 v40, 0xffff0000, v56
	v_lshlrev_b32_e32 v56, 16, v41
	v_lshlrev_b32_e32 v71, 16, v57
	v_and_b32_e32 v72, 0xffff0000, v41
	v_and_b32_e32 v41, 0xffff0000, v57
	v_lshlrev_b32_e32 v57, 16, v42
	v_lshlrev_b32_e32 v73, 16, v58
	v_and_b32_e32 v74, 0xffff0000, v42
	v_and_b32_e32 v42, 0xffff0000, v58
	v_lshlrev_b32_e32 v58, 16, v43
	v_lshlrev_b32_e32 v75, 16, v59
	v_and_b32_e32 v76, 0xffff0000, v43
	v_and_b32_e32 v43, 0xffff0000, v59
	v_fmac_f32_e32 v68, v28, v69
	v_fmac_f32_e32 v70, v29, v40
	v_fmac_f32_e32 v56, v30, v71
	v_fmac_f32_e32 v72, v31, v41
	v_fmac_f32_e32 v57, v24, v73
	v_fmac_f32_e32 v74, v25, v42
	v_fmac_f32_e32 v58, v26, v75
	v_fmac_f32_e32 v76, v27, v43
	v_cvt_pk_bf16_f32 v24, v68, v70
	v_cvt_pk_bf16_f32 v25, v56, v72
	v_cvt_pk_bf16_f32 v26, v57, v74
	v_cvt_pk_bf16_f32 v27, v58, v76
	v_mul_f32_e32 v28, v52, v68
	v_mul_f32_e32 v29, v53, v70
	v_mul_f32_e32 v30, v54, v56
	v_mul_f32_e32 v31, v55, v72
	v_mul_f32_e32 v40, v48, v57
	v_mul_f32_e32 v41, v49, v74
	v_mul_f32_e32 v42, v50, v58
	v_mul_f32_e32 v43, v51, v76
	global_store_dwordx4 v[60:61], v[24:27], off
	v_mul_f32_e32 v59, v70, v70
	v_fmac_f32_e32 v59, v68, v68
	v_cvt_pk_bf16_f32 v24, v28, v29
	v_cvt_pk_bf16_f32 v25, v30, v31
	v_cvt_pk_bf16_f32 v26, v40, v41
	v_cvt_pk_bf16_f32 v27, v42, v43
	global_load_dwordx4 v[28:31], v[64:65], off
	global_load_dwordx4 v[40:43], v[66:67], off
	v_fmac_f32_e32 v59, v56, v56
	v_fmac_f32_e32 v59, v72, v72
	v_fmac_f32_e32 v59, v57, v57
	v_fmac_f32_e32 v59, v74, v74
	global_store_dwordx4 v[62:63], v[24:27], off
	v_fmac_f32_e32 v59, v58, v58
	v_fmac_f32_e32 v59, v76, v76
	s_waitcnt vmcnt(2)
	v_lshlrev_b32_e32 v24, 16, v28
	s_waitcnt vmcnt(1)
	v_lshlrev_b32_e32 v25, 16, v40
	v_and_b32_e32 v26, 0xffff0000, v28
	v_and_b32_e32 v27, 0xffff0000, v40
	v_fmac_f32_e32 v24, v20, v25
	v_lshlrev_b32_e32 v28, 16, v29
	v_lshlrev_b32_e32 v40, 16, v41
	v_fmac_f32_e32 v26, v21, v27
	v_fmac_f32_e32 v59, v24, v24
	v_and_b32_e32 v29, 0xffff0000, v29
	v_and_b32_e32 v41, 0xffff0000, v41
	v_fmac_f32_e32 v28, v22, v40
	v_fmac_f32_e32 v59, v26, v26
	v_lshlrev_b32_e32 v56, 16, v30
	v_lshlrev_b32_e32 v57, 16, v42
	v_fmac_f32_e32 v29, v23, v41
	v_fmac_f32_e32 v59, v28, v28
	v_and_b32_e32 v30, 0xffff0000, v30
	v_and_b32_e32 v42, 0xffff0000, v42
	v_fmac_f32_e32 v56, v16, v57
	v_fmac_f32_e32 v59, v29, v29
	v_lshlrev_b32_e32 v58, 16, v31
	v_lshlrev_b32_e32 v60, 16, v43
	v_fmac_f32_e32 v30, v17, v42
	v_fmac_f32_e32 v59, v56, v56
	v_and_b32_e32 v31, 0xffff0000, v31
	v_and_b32_e32 v43, 0xffff0000, v43
	v_fmac_f32_e32 v58, v18, v60
	v_fmac_f32_e32 v59, v30, v30
	v_fmac_f32_e32 v31, v19, v43
	v_fmac_f32_e32 v59, v58, v58
	v_cvt_pk_bf16_f32 v16, v24, v26
	v_fmac_f32_e32 v59, v31, v31
	v_cvt_pk_bf16_f32 v17, v28, v29
	v_cvt_pk_bf16_f32 v18, v56, v30
	v_cvt_pk_bf16_f32 v19, v58, v31
	global_store_dwordx4 v[64:65], v[16:19], off
	ds_bpermute_b32 v16, v132, v59
	v_mul_f32_e32 v20, v44, v24
	v_mul_f32_e32 v21, v45, v26
	v_cvt_pk_bf16_f32 v18, v20, v21
	v_mul_f32_e32 v17, v36, v56
	v_mul_f32_e32 v20, v37, v30
	s_waitcnt lgkmcnt(0)
	v_add_f32_e32 v16, v59, v16
	v_mul_f32_e32 v22, v46, v28
	v_mul_f32_e32 v23, v47, v29
	v_cvt_pk_bf16_f32 v19, v22, v23
	v_cvt_pk_bf16_f32 v20, v17, v20
	ds_bpermute_b32 v17, v133, v16
	v_mul_f32_e32 v21, v38, v58
	v_mul_f32_e32 v22, v39, v31
	v_cvt_pk_bf16_f32 v21, v21, v22
	v_lshl_add_u64 v[22:23], s[12:13], 0, v[34:35]
	global_store_dwordx4 v[22:23], v[18:21], off
	s_and_saveexec_b64 s[54:55], s[4:5]
	s_cbranch_execz .LBB0_853
	v_lshl_add_u64 v[18:19], v[32:33], 2, s[18:19]
	s_waitcnt lgkmcnt(0)
	v_add_f32_e32 v16, v16, v17
	v_mov_b32_e32 v236, v16
;     __device__ __forceinline__ void operator()(const f32x4 (&acc)[2][2][4][2], const Unit& u, int wr, int wc, int fr, int fq) const {
;     ...
;             for (int m = 0; m < 4; ++m) { const int row = row0 + ai * HALF + m * 16; const size_t off = (size_t)row * 1024 + col0; float rs = 0.f;
; #pragma unroll
;                 for (int bj = 0; bj < 2; ++bj) { const size_t c = off + bj * HALF;
;                     const u32x4 hw = *(const u32x4*)(Hin + c); const u32x4 pw = *(const u32x4*)(PP + c);
;                     float o[8];
; #pragma unroll
;                     for (int n = 0; n < 2; ++n)
; #pragma unroll
;                         for (int w = 0; w < 2; ++w) { const unsigned hh = hw[2 * n + w], pp = pw[2 * n + w]; const f32x4 a = acc[ai][bj][m][n];
;                             o[4 * n + 2 * w] = bf_lo(hh) + bf_lo(pp) * sigmoid_f(a[2 * w]); o[4 * n + 2 * w + 1] = bf_hi(hh) + bf_hi(pp) * sigmoid_f(a[2 * w + 1]); }
;                     if (MODE == 1) { *(f32x4*)(Fout + c) = (f32x4){o[0], o[1], o[2], o[3]}; *(f32x4*)(Fout + c + 4) = (f32x4){o[4], o[5], o[6], o[7]}; }
;                     else { u32x4 w; w.x = cvt_pk_bf16(o[0], o[1]); w.y = cvt_pk_bf16(o[2], o[3]); w.z = cvt_pk_bf16(o[4], o[5]); w.w = cvt_pk_bf16(o[6], o[7]); *(u32x4*)(Hout + c) = w; }
;                     if (MODE == 2) {
; #pragma unroll
;                         for (int e = 0; e < 8; ++e) rs += o[e] * o[e];
;                         u32x4 w; w.x = cvt_pk_bf16(o[0] * gp[bj][0], o[1] * gp[bj][1]); w.y = cvt_pk_bf16(o[2] * gp[bj][2], o[3] * gp[bj][3]);
;                         w.z = cvt_pk_bf16(o[4] * gp[bj][4], o[5] * gp[bj][5]); w.w = cvt_pk_bf16(o[6] * gp[bj][6], o[7] * gp[bj][7]); *(u32x4*)(A2 + c) = w; } }
;                 if (MODE == 2) { rs += __shfl_xor(rs, 16); rs += __shfl_xor(rs, 32); if (fq == 0) atomicAdd(SS + row, rs); } }
; template <class Epi, class Sched, bool ALIGN_EPI = false, bool SP2 = false>
; __device__ __forceinline__ void gemm_phase(PG8_LAS unsigned char* lds, const Gemm g, const Sched& S, const Epi& E) {
;     ...
;         if constexpr (ALIGN_EPI) { if (wr == 0) PG8_BAR; }
;         if constexpr (!Epi::AFTER_DRAIN) { E(acc, cur, wr, wc, fr, fq); S.done(cur); }
;         if (!has_next) break;
; #pragma unroll
;         for (int a = 0; a < 2; ++a)
; #pragma unroll
;             for (int b = 0; b < 2; ++b)
; #pragma unroll
;                 for (int m = 0; m < 4; ++m)
.LBB0_853:
	s_or_b64 exec, exec, s[54:55]
	v_add_u32_e32 v16, 0xb0, v154
	s_waitcnt lgkmcnt(0)
	v_ashrrev_i32_e32 v17, 31, v16
	v_lshlrev_b64 v[18:19], 10, v[16:17]
	v_lshl_add_u64 v[18:19], v[18:19], 0, v[152:153]
	v_lshlrev_b64 v[18:19], 1, v[18:19]
	v_lshl_add_u64 v[28:29], s[16:17], 0, v[18:19]
	v_lshl_add_u64 v[24:25], s[36:37], 0, v[18:19]
	global_load_dwordx4 v[20:23], v[28:29], off
	s_nop 0
	global_load_dwordx4 v[24:27], v[24:25], off
	v_mul_f32_e32 v12, 0xbfb8aa3b, v12
	v_mul_f32_e32 v13, 0xbfb8aa3b, v13
	v_mul_f32_e32 v14, 0xbfb8aa3b, v14
	v_mul_f32_e32 v15, 0xbfb8aa3b, v15
	v_mul_f32_e32 v8, 0xbfb8aa3b, v8
	v_mul_f32_e32 v9, 0xbfb8aa3b, v9
	v_mul_f32_e32 v10, 0xbfb8aa3b, v10
	v_mul_f32_e32 v11, 0xbfb8aa3b, v11
	v_exp_f32_e32 v12, v12
	v_exp_f32_e32 v13, v13
	v_exp_f32_e32 v14, v14
	v_exp_f32_e32 v15, v15
	v_exp_f32_e32 v8, v8
	v_exp_f32_e32 v9, v9
	v_exp_f32_e32 v10, v10
	v_exp_f32_e32 v11, v11
	v_add_f32_e32 v12, 1.0, v12
	v_add_f32_e32 v13, 1.0, v13
	v_add_f32_e32 v14, 1.0, v14
	v_add_f32_e32 v15, 1.0, v15
	v_add_f32_e32 v8, 1.0, v8
	v_add_f32_e32 v9, 1.0, v9
	v_add_f32_e32 v10, 1.0, v10
	v_add_f32_e32 v11, 1.0, v11
	v_rcp_f32_e32 v12, v12
	v_rcp_f32_e32 v13, v13
	v_rcp_f32_e32 v14, v14
	v_rcp_f32_e32 v15, v15
	v_rcp_f32_e32 v8, v8
	v_rcp_f32_e32 v9, v9
	v_rcp_f32_e32 v10, v10
	v_rcp_f32_e32 v11, v11
	v_lshl_add_u64 v[30:31], s[12:13], 0, v[18:19]
	v_or_b32_e32 v18, 0x100, v18
	v_lshl_add_u64 v[32:33], s[16:17], 0, v[18:19]
	v_lshl_add_u64 v[34:35], s[36:37], 0, v[18:19]
	v_mul_f32_e32 v4, 0xbfb8aa3b, v4
	v_mul_f32_e32 v5, 0xbfb8aa3b, v5
	v_exp_f32_e32 v4, v4
	v_mul_f32_e32 v6, 0xbfb8aa3b, v6
	v_exp_f32_e32 v5, v5
	v_mul_f32_e32 v7, 0xbfb8aa3b, v7
	v_exp_f32_e32 v6, v6
	v_mul_f32_e32 v0, 0xbfb8aa3b, v0
	v_exp_f32_e32 v7, v7
	v_mul_f32_e32 v1, 0xbfb8aa3b, v1
	v_exp_f32_e32 v0, v0
	v_add_f32_e32 v4, 1.0, v4
	v_mul_f32_e32 v2, 0xbfb8aa3b, v2
	v_exp_f32_e32 v1, v1
	v_add_f32_e32 v5, 1.0, v5
	v_rcp_f32_e32 v4, v4
	v_mul_f32_e32 v3, 0xbfb8aa3b, v3
	v_exp_f32_e32 v2, v2
	v_add_f32_e32 v6, 1.0, v6
	v_rcp_f32_e32 v5, v5
	v_exp_f32_e32 v3, v3
	v_add_f32_e32 v7, 1.0, v7
	v_rcp_f32_e32 v6, v6
	v_add_f32_e32 v0, 1.0, v0
	v_rcp_f32_e32 v7, v7
	v_add_f32_e32 v1, 1.0, v1
	v_rcp_f32_e32 v0, v0
	v_add_f32_e32 v2, 1.0, v2
	v_rcp_f32_e32 v1, v1
	v_add_f32_e32 v3, 1.0, v3
	v_rcp_f32_e32 v2, v2
	v_rcp_f32_e32 v3, v3
	s_waitcnt vmcnt(1)
	v_lshlrev_b32_e32 v40, 16, v20
	s_waitcnt vmcnt(0)
	v_lshlrev_b32_e32 v41, 16, v24
	v_and_b32_e32 v42, 0xffff0000, v20
	v_and_b32_e32 v20, 0xffff0000, v24
	v_lshlrev_b32_e32 v24, 16, v21
	v_lshlrev_b32_e32 v43, 16, v25
	v_and_b32_e32 v56, 0xffff0000, v21
	v_and_b32_e32 v21, 0xffff0000, v25
	v_lshlrev_b32_e32 v25, 16, v22
	v_lshlrev_b32_e32 v57, 16, v26
	v_and_b32_e32 v58, 0xffff0000, v22
	v_and_b32_e32 v22, 0xffff0000, v26
	v_lshlrev_b32_e32 v26, 16, v23
	v_lshlrev_b32_e32 v59, 16, v27
	v_and_b32_e32 v60, 0xffff0000, v23
	v_and_b32_e32 v23, 0xffff0000, v27
	v_fmac_f32_e32 v40, v12, v41
	v_fmac_f32_e32 v42, v13, v20
	v_fmac_f32_e32 v24, v14, v43
	v_fmac_f32_e32 v56, v15, v21
	v_fmac_f32_e32 v25, v8, v57
	v_fmac_f32_e32 v58, v9, v22
	v_fmac_f32_e32 v26, v10, v59
	v_fmac_f32_e32 v60, v11, v23
	v_cvt_pk_bf16_f32 v8, v40, v42
	v_cvt_pk_bf16_f32 v9, v24, v56
	v_cvt_pk_bf16_f32 v10, v25, v58
	v_cvt_pk_bf16_f32 v11, v26, v60
	v_mul_f32_e32 v12, v52, v40
	v_mul_f32_e32 v13, v53, v42
	v_mul_f32_e32 v14, v54, v24
	v_mul_f32_e32 v15, v55, v56
	v_mul_f32_e32 v20, v48, v25
	v_mul_f32_e32 v21, v49, v58
	v_mul_f32_e32 v22, v50, v26
	v_mul_f32_e32 v23, v51, v60
	global_store_dwordx4 v[28:29], v[8:11], off
	v_mul_f32_e32 v27, v42, v42
	v_fmac_f32_e32 v27, v40, v40
	v_cvt_pk_bf16_f32 v8, v12, v13
	v_cvt_pk_bf16_f32 v9, v14, v15
	v_cvt_pk_bf16_f32 v10, v20, v21
	v_cvt_pk_bf16_f32 v11, v22, v23
	global_load_dwordx4 v[12:15], v[32:33], off
	global_load_dwordx4 v[20:23], v[34:35], off
	v_fmac_f32_e32 v27, v24, v24
	v_fmac_f32_e32 v27, v56, v56
	v_fmac_f32_e32 v27, v25, v25
	v_fmac_f32_e32 v27, v58, v58
	global_store_dwordx4 v[30:31], v[8:11], off
	v_fmac_f32_e32 v27, v26, v26
	v_fmac_f32_e32 v27, v60, v60
	s_waitcnt vmcnt(2)
	v_lshlrev_b32_e32 v8, 16, v12
	s_waitcnt vmcnt(1)
	v_lshlrev_b32_e32 v9, 16, v20
	v_and_b32_e32 v10, 0xffff0000, v12
	v_and_b32_e32 v11, 0xffff0000, v20
	v_fmac_f32_e32 v8, v4, v9
	v_lshlrev_b32_e32 v12, 16, v13
	v_lshlrev_b32_e32 v20, 16, v21
	v_fmac_f32_e32 v10, v5, v11
	v_fmac_f32_e32 v27, v8, v8
	v_and_b32_e32 v13, 0xffff0000, v13
	v_and_b32_e32 v21, 0xffff0000, v21
	v_fmac_f32_e32 v12, v6, v20
	v_fmac_f32_e32 v27, v10, v10
	v_lshlrev_b32_e32 v24, 16, v14
	v_lshlrev_b32_e32 v25, 16, v22
	v_fmac_f32_e32 v13, v7, v21
	v_fmac_f32_e32 v27, v12, v12
	v_and_b32_e32 v14, 0xffff0000, v14
	v_and_b32_e32 v22, 0xffff0000, v22
	v_fmac_f32_e32 v24, v0, v25
	v_fmac_f32_e32 v27, v13, v13
	v_lshlrev_b32_e32 v26, 16, v15
	v_lshlrev_b32_e32 v28, 16, v23
	v_fmac_f32_e32 v14, v1, v22
	v_fmac_f32_e32 v27, v24, v24
	v_and_b32_e32 v15, 0xffff0000, v15
	v_and_b32_e32 v23, 0xffff0000, v23
	v_fmac_f32_e32 v26, v2, v28
	v_fmac_f32_e32 v27, v14, v14
	v_fmac_f32_e32 v15, v3, v23
	v_fmac_f32_e32 v27, v26, v26
	v_cvt_pk_bf16_f32 v0, v8, v10
	v_fmac_f32_e32 v27, v15, v15
	v_cvt_pk_bf16_f32 v1, v12, v13
	v_cvt_pk_bf16_f32 v2, v24, v14
	v_cvt_pk_bf16_f32 v3, v26, v15
	global_store_dwordx4 v[32:33], v[0:3], off
	ds_bpermute_b32 v0, v132, v27
	v_mul_f32_e32 v4, v44, v8
	v_mul_f32_e32 v5, v45, v10
	v_cvt_pk_bf16_f32 v2, v4, v5
	v_mul_f32_e32 v1, v36, v24
	v_mul_f32_e32 v4, v37, v14
	s_waitcnt lgkmcnt(0)
	v_add_f32_e32 v0, v27, v0
	v_mul_f32_e32 v6, v46, v12
	v_mul_f32_e32 v7, v47, v13
	v_cvt_pk_bf16_f32 v3, v6, v7
	v_cvt_pk_bf16_f32 v4, v1, v4
	ds_bpermute_b32 v1, v133, v0
	v_mul_f32_e32 v5, v38, v26
	v_mul_f32_e32 v6, v39, v15
	v_cvt_pk_bf16_f32 v5, v5, v6
	v_lshl_add_u64 v[6:7], s[12:13], 0, v[18:19]
	global_store_dwordx4 v[6:7], v[2:5], off
	s_and_saveexec_b64 s[54:55], s[4:5]
	s_cbranch_execz .LBB0_855
	v_lshl_add_u64 v[2:3], v[16:17], 2, s[18:19]
	s_waitcnt lgkmcnt(0)
	v_add_f32_e32 v0, v0, v1
	v_mov_b32_e32 v237, v0
.LBB0_855:
	s_or_b64 exec, exec, s[54:55]
	s_and_saveexec_b64 s[54:55], s[4:5]
	global_atomic_add_f32 v[228:229], v230, off
	global_atomic_add_f32 v[228:229], v231, off offset:64
	global_atomic_add_f32 v[228:229], v232, off offset:128
	global_atomic_add_f32 v[228:229], v233, off offset:192
	global_atomic_add_f32 v[228:229], v234, off offset:512
	global_atomic_add_f32 v[228:229], v235, off offset:576
	global_atomic_add_f32 v[228:229], v236, off offset:640
	global_atomic_add_f32 v[228:229], v237, off offset:704
	s_or_b64 exec, exec, s[54:55]
	s_andn2_b64 vcc, exec, s[6:7]
	s_mov_b64 s[6:7], -1
	s_cbranch_vccnz .LBB0_828
	s_andn2_b64 vcc, exec, s[0:1]
	s_cbranch_vccnz .LBB0_827
	s_barrier
	s_branch .LBB0_827

; __device__ __forceinline__ unsigned cvt_pk_bf16(float lo, float hi) { unsigned r; asm volatile("v_cvt_pk_bf16_f32 %0, %1, %2" : "=v"(r) : "v"(lo), "v"(hi)); return r; }
;     __device__ __forceinline__ void operator()(const f32x4 (&acc)[2][2][4][2], const Unit& u, int wr, int wc, int fr, int fq) const {
;     ...
;             for (int m = 0; m < 4; ++m) { const int row = row0 + ai * HALF + m * 16; bf16_t* rowp = O + (size_t)row * ldc + col0;
;                 float sc = sc0; if (ROWSCALE) sc *= 1.0f / sqrtf(SS[row] * (1.0f / 1024.0f) + 1e-6f);
; #pragma unroll
;                 for (int bj = 0; bj < 2; ++bj) { const f32x4 v0 = acc[ai][bj][m][0] * sc, v1 = acc[ai][bj][m][1] * sc;
;                     u32x4 w; w.x = cvt_pk_bf16(v0[0], v0[1]); w.y = cvt_pk_bf16(v0[2], v0[3]); w.z = cvt_pk_bf16(v1[0], v1[1]); w.w = cvt_pk_bf16(v1[2], v1[3]);
;                     *(u32x4*)(rowp + bj * HALF) = w; } }
.LBB0_937:
	v_lshl_add_u32 v148, s0, 8, v152
	v_ashrrev_i32_e32 v149, 31, v148
	v_lshl_add_u64 v[144:145], v[148:149], 2, s[12:13]
	global_load_dword v161, v[144:145], off
	global_load_dword v231, v[144:145], off offset:64
	global_load_dword v232, v[144:145], off offset:128
	global_load_dword v233, v[144:145], off offset:192
	global_load_dword v234, v[144:145], off offset:512
	global_load_dword v235, v[144:145], off offset:576
	global_load_dword v236, v[144:145], off offset:640
	global_load_dword v237, v[144:145], off offset:704
	v_lshl_or_b32 v146, s1, 8, v154
	v_ashrrev_i32_e32 v147, 31, v146
	v_lshlrev_b64 v[150:151], 1, v[146:147]
	v_lshlrev_b64 v[164:165], 12, v[148:149]
	v_or_b32_e32 v162, 16, v148
	v_ashrrev_i32_e32 v163, 31, v162
	s_waitcnt vmcnt(0)
	v_fmamk_f32 v146, v161, 0x3a800000, v158
	v_mul_f32_e32 v147, 0x4f800000, v146
	v_cmp_gt_f32_e32 vcc, s87, v146
	s_nop 1
	v_cndmask_b32_e32 v149, v146, v147, vcc
	v_sqrt_f32_e32 v161, v149
	v_lshl_add_u64 v[146:147], s[40:41], 0, v[164:165]
	v_lshl_add_u64 v[146:147], v[146:147], 0, v[150:151]
	v_lshl_add_u64 v[164:165], v[162:163], 2, s[12:13]
	v_add_u32_e32 v166, -1, v161
	v_add_u32_e32 v167, 1, v161
	v_fma_f32 v168, -v166, v161, v149
	v_fma_f32 v169, -v167, v161, v149
	v_cmp_ge_f32_e64 s[0:1], 0, v168
	s_nop 1
	v_cndmask_b32_e64 v161, v161, v166, s[0:1]
	v_cmp_lt_f32_e64 s[0:1], 0, v169
	s_nop 1
	v_cndmask_b32_e64 v161, v161, v167, s[0:1]
	v_mul_f32_e32 v166, 0x37800000, v161
	v_cndmask_b32_e32 v161, v161, v166, vcc
	v_cmp_class_f32_e32 vcc, v149, v159
	s_nop 1
	v_cndmask_b32_e32 v149, v161, v149, vcc
	v_div_scale_f32 v161, s[0:1], v149, v149, 1.0
	v_rcp_f32_e32 v166, v161
	v_div_scale_f32 v167, vcc, 1.0, v149, 1.0
	v_fma_f32 v168, -v161, v166, 1.0
	v_fmac_f32_e32 v166, v168, v166
	v_mul_f32_e32 v168, v167, v166
	v_fma_f32 v169, -v161, v168, v167
	v_fmac_f32_e32 v168, v169, v166
	v_fma_f32 v161, -v161, v168, v167
	v_div_fmas_f32 v161, v161, v166, v168
	v_div_fixup_f32 v166, v161, v149, 1.0
	v_mul_f32_e32 v126, v126, v166
	v_mul_f32_e32 v127, v127, v166
	v_mul_f32_e32 v124, v124, v166
	v_mul_f32_e32 v125, v125, v166
	v_mul_f32_e32 v122, v122, v166
	v_mul_f32_e32 v123, v123, v166
	v_mul_f32_e32 v120, v120, v166
	v_mul_f32_e32 v121, v121, v166
	v_mul_f32_e32 v118, v118, v166
	v_mul_f32_e32 v119, v119, v166
	v_mul_f32_e32 v116, v116, v166
	v_mul_f32_e32 v117, v117, v166
	v_mul_f32_e32 v168, v114, v166
	v_mul_f32_e32 v169, v115, v166
	v_mul_f32_e32 v167, v113, v166
	v_mul_f32_e32 v166, v112, v166
	v_cvt_pk_bf16_f32 v112, v124, v125
	v_cvt_pk_bf16_f32 v113, v126, v127
	v_cvt_pk_bf16_f32 v114, v120, v121
	v_cvt_pk_bf16_f32 v115, v122, v123
	global_store_dwordx4 v[146:147], v[112:115], off
	s_nop 1
	v_cvt_pk_bf16_f32 v112, v116, v117
	v_cvt_pk_bf16_f32 v113, v118, v119
	v_cvt_pk_bf16_f32 v114, v166, v167
	v_cvt_pk_bf16_f32 v115, v168, v169
	global_store_dwordx4 v[146:147], v[112:115], off offset:256
	s_nop 1
	s_nop 0
	v_or_b32_e32 v112, 32, v148
	v_ashrrev_i32_e32 v113, 31, v112
	v_lshl_add_u64 v[116:117], v[112:113], 2, s[12:13]
	v_mov_b32_e32 v114, v231
	v_fmamk_f32 v114, v114, 0x3a800000, v158
	v_mul_f32_e32 v115, 0x4f800000, v114
	v_cmp_gt_f32_e32 vcc, s87, v114
	s_nop 1
	v_cndmask_b32_e32 v118, v114, v115, vcc
	v_sqrt_f32_e32 v119, v118
	v_lshlrev_b64 v[114:115], 12, v[162:163]
	v_lshl_add_u64 v[114:115], s[40:41], 0, v[114:115]
	v_lshl_add_u64 v[114:115], v[114:115], 0, v[150:151]
	v_add_u32_e32 v120, -1, v119
	v_add_u32_e32 v121, 1, v119
	v_fma_f32 v122, -v120, v119, v118
	v_fma_f32 v123, -v121, v119, v118
	v_cmp_ge_f32_e64 s[0:1], 0, v122
	s_nop 1
	v_cndmask_b32_e64 v119, v119, v120, s[0:1]
	v_cmp_lt_f32_e64 s[0:1], 0, v123
	s_nop 1
	v_cndmask_b32_e64 v119, v119, v121, s[0:1]
	v_mul_f32_e32 v120, 0x37800000, v119
	v_cndmask_b32_e32 v119, v119, v120, vcc
	v_cmp_class_f32_e32 vcc, v118, v159
	s_nop 1
	v_cndmask_b32_e32 v118, v119, v118, vcc
	v_div_scale_f32 v119, s[0:1], v118, v118, 1.0
	v_rcp_f32_e32 v120, v119
	v_div_scale_f32 v121, vcc, 1.0, v118, 1.0
	v_fma_f32 v122, -v119, v120, 1.0
	v_fmac_f32_e32 v120, v122, v120
	v_mul_f32_e32 v122, v121, v120
	v_fma_f32 v123, -v119, v122, v121
	v_fmac_f32_e32 v122, v123, v120
	v_fma_f32 v119, -v119, v122, v121
	v_div_fmas_f32 v119, v119, v120, v122
	v_div_fixup_f32 v118, v119, v118, 1.0
	v_mul_f32_e32 v110, v110, v118
	v_mul_f32_e32 v111, v111, v118
	v_mul_f32_e32 v108, v108, v118
	v_mul_f32_e32 v109, v109, v118
	v_mul_f32_e32 v106, v106, v118
	v_mul_f32_e32 v107, v107, v118
	v_mul_f32_e32 v104, v104, v118
	v_mul_f32_e32 v105, v105, v118
	v_mul_f32_e32 v102, v102, v118
	v_mul_f32_e32 v103, v103, v118
	v_mul_f32_e32 v100, v100, v118
	v_mul_f32_e32 v101, v101, v118
	v_mul_f32_e32 v120, v98, v118
	v_mul_f32_e32 v121, v99, v118
	v_mul_f32_e32 v119, v97, v118
	v_mul_f32_e32 v118, v96, v118
	v_cvt_pk_bf16_f32 v96, v108, v109
	v_cvt_pk_bf16_f32 v97, v110, v111
	v_cvt_pk_bf16_f32 v98, v104, v105
	v_cvt_pk_bf16_f32 v99, v106, v107
	global_store_dwordx4 v[114:115], v[96:99], off
	s_nop 1
	v_cvt_pk_bf16_f32 v96, v100, v101
	v_cvt_pk_bf16_f32 v97, v102, v103
	v_cvt_pk_bf16_f32 v98, v118, v119
	v_cvt_pk_bf16_f32 v99, v120, v121
	global_store_dwordx4 v[114:115], v[96:99], off offset:256
	s_nop 1
	s_nop 0
	v_or_b32_e32 v96, 48, v148
	v_ashrrev_i32_e32 v97, 31, v96
	v_lshl_add_u64 v[100:101], v[96:97], 2, s[12:13]
	v_mov_b32_e32 v98, v232
	v_fmamk_f32 v98, v98, 0x3a800000, v158
	v_mul_f32_e32 v99, 0x4f800000, v98
	v_cmp_gt_f32_e32 vcc, s87, v98
	s_nop 1
	v_cndmask_b32_e32 v102, v98, v99, vcc
	v_sqrt_f32_e32 v103, v102
	v_lshlrev_b64 v[98:99], 12, v[112:113]
	v_lshl_add_u64 v[98:99], s[40:41], 0, v[98:99]
	v_lshl_add_u64 v[98:99], v[98:99], 0, v[150:151]
; __device__ __forceinline__ unsigned cvt_pk_bf16(float lo, float hi) { unsigned r; asm volatile("v_cvt_pk_bf16_f32 %0, %1, %2" : "=v"(r) : "v"(lo), "v"(hi)); return r; }
;     __device__ __forceinline__ void operator()(const f32x4 (&acc)[2][2][4][2], const Unit& u, int wr, int wc, int fr, int fq) const {
;     ...
;             for (int m = 0; m < 4; ++m) { const int row = row0 + ai * HALF + m * 16; bf16_t* rowp = O + (size_t)row * ldc + col0;
;                 float sc = sc0; if (ROWSCALE) sc *= 1.0f / sqrtf(SS[row] * (1.0f / 1024.0f) + 1e-6f);
; #pragma unroll
;                 for (int bj = 0; bj < 2; ++bj) { const f32x4 v0 = acc[ai][bj][m][0] * sc, v1 = acc[ai][bj][m][1] * sc;
;                     u32x4 w; w.x = cvt_pk_bf16(v0[0], v0[1]); w.y = cvt_pk_bf16(v0[2], v0[3]); w.z = cvt_pk_bf16(v1[0], v1[1]); w.w = cvt_pk_bf16(v1[2], v1[3]);
;                     *(u32x4*)(rowp + bj * HALF) = w; } }
	v_add_u32_e32 v104, -1, v103
	v_add_u32_e32 v105, 1, v103
	v_fma_f32 v106, -v104, v103, v102
	v_fma_f32 v107, -v105, v103, v102
	v_cmp_ge_f32_e64 s[0:1], 0, v106
	s_nop 1
	v_cndmask_b32_e64 v103, v103, v104, s[0:1]
	v_cmp_lt_f32_e64 s[0:1], 0, v107
	s_nop 1
	v_cndmask_b32_e64 v103, v103, v105, s[0:1]
	v_mul_f32_e32 v104, 0x37800000, v103
	v_cndmask_b32_e32 v103, v103, v104, vcc
	v_cmp_class_f32_e32 vcc, v102, v159
	s_nop 1
	v_cndmask_b32_e32 v102, v103, v102, vcc
	v_div_scale_f32 v103, s[0:1], v102, v102, 1.0
	v_rcp_f32_e32 v104, v103
	v_div_scale_f32 v105, vcc, 1.0, v102, 1.0
	v_fma_f32 v106, -v103, v104, 1.0
	v_fmac_f32_e32 v104, v106, v104
	v_mul_f32_e32 v106, v105, v104
	v_fma_f32 v107, -v103, v106, v105
	v_fmac_f32_e32 v106, v107, v104
	v_fma_f32 v103, -v103, v106, v105
	v_div_fmas_f32 v103, v103, v104, v106
	v_div_fixup_f32 v102, v103, v102, 1.0
	v_mul_f32_e32 v94, v94, v102
	v_mul_f32_e32 v95, v95, v102
	v_mul_f32_e32 v92, v92, v102
	v_mul_f32_e32 v93, v93, v102
	v_mul_f32_e32 v90, v90, v102
	v_mul_f32_e32 v91, v91, v102
	v_mul_f32_e32 v88, v88, v102
	v_mul_f32_e32 v89, v89, v102
	v_mul_f32_e32 v86, v86, v102
	v_mul_f32_e32 v87, v87, v102
	v_mul_f32_e32 v84, v84, v102
	v_mul_f32_e32 v85, v85, v102
	v_mul_f32_e32 v104, v82, v102
	v_mul_f32_e32 v105, v83, v102
	v_mul_f32_e32 v103, v81, v102
	v_mul_f32_e32 v102, v80, v102
	v_cvt_pk_bf16_f32 v80, v92, v93
	v_cvt_pk_bf16_f32 v81, v94, v95
	v_cvt_pk_bf16_f32 v82, v88, v89
	v_cvt_pk_bf16_f32 v83, v90, v91
	global_store_dwordx4 v[98:99], v[80:83], off
	s_nop 1
	v_cvt_pk_bf16_f32 v80, v84, v85
	v_cvt_pk_bf16_f32 v81, v86, v87
	v_cvt_pk_bf16_f32 v82, v102, v103
	v_cvt_pk_bf16_f32 v83, v104, v105
	global_store_dwordx4 v[98:99], v[80:83], off offset:256
	s_nop 1
	v_mov_b32_e32 v80, v233
	v_fmamk_f32 v80, v80, 0x3a800000, v158
	v_mul_f32_e32 v81, 0x4f800000, v80
	v_cmp_gt_f32_e32 vcc, s87, v80
	s_nop 1
	v_cndmask_b32_e32 v82, v80, v81, vcc
	v_sqrt_f32_e32 v83, v82
	v_lshlrev_b64 v[80:81], 12, v[96:97]
	v_lshl_add_u64 v[80:81], s[40:41], 0, v[80:81]
	v_lshl_add_u64 v[80:81], v[80:81], 0, v[150:151]
	v_add_u32_e32 v84, -1, v83
	v_add_u32_e32 v85, 1, v83
	v_fma_f32 v86, -v84, v83, v82
	v_fma_f32 v87, -v85, v83, v82
	v_cmp_ge_f32_e64 s[0:1], 0, v86
	s_nop 1
	v_cndmask_b32_e64 v83, v83, v84, s[0:1]
	v_cmp_lt_f32_e64 s[0:1], 0, v87
	s_nop 1
	v_cndmask_b32_e64 v83, v83, v85, s[0:1]
	v_mul_f32_e32 v84, 0x37800000, v83
	v_cndmask_b32_e32 v83, v83, v84, vcc
	v_cmp_class_f32_e32 vcc, v82, v159
	s_nop 1
	v_cndmask_b32_e32 v82, v83, v82, vcc
	v_div_scale_f32 v83, s[0:1], v82, v82, 1.0
	v_rcp_f32_e32 v84, v83
	v_div_scale_f32 v85, vcc, 1.0, v82, 1.0
	v_fma_f32 v86, -v83, v84, 1.0
	v_fmac_f32_e32 v84, v86, v84
	v_mul_f32_e32 v86, v85, v84
	v_fma_f32 v87, -v83, v86, v85
	v_fmac_f32_e32 v86, v87, v84
	v_fma_f32 v83, -v83, v86, v85
	v_div_fmas_f32 v83, v83, v84, v86
	v_div_fixup_f32 v82, v83, v82, 1.0
	v_mul_f32_e32 v78, v78, v82
	v_mul_f32_e32 v79, v79, v82
	v_mul_f32_e32 v76, v76, v82
	v_mul_f32_e32 v77, v77, v82
	v_mul_f32_e32 v74, v74, v82
	v_mul_f32_e32 v75, v75, v82
	v_mul_f32_e32 v72, v72, v82
	v_mul_f32_e32 v73, v73, v82
	v_mul_f32_e32 v70, v70, v82
	v_mul_f32_e32 v71, v71, v82
	v_mul_f32_e32 v68, v68, v82
	v_mul_f32_e32 v69, v69, v82
	v_mul_f32_e32 v84, v66, v82
	v_mul_f32_e32 v85, v67, v82
	v_mul_f32_e32 v83, v65, v82
	v_mul_f32_e32 v82, v64, v82
	v_cvt_pk_bf16_f32 v64, v76, v77
	v_cvt_pk_bf16_f32 v65, v78, v79
	v_cvt_pk_bf16_f32 v66, v72, v73
	v_cvt_pk_bf16_f32 v67, v74, v75
	global_store_dwordx4 v[80:81], v[64:67], off
	s_nop 1
	v_cvt_pk_bf16_f32 v64, v68, v69
	v_cvt_pk_bf16_f32 v65, v70, v71
	v_cvt_pk_bf16_f32 v66, v82, v83
	v_cvt_pk_bf16_f32 v67, v84, v85
	global_store_dwordx4 v[80:81], v[64:67], off offset:256
	s_nop 1
	v_mov_b32_e32 v64, v234
	v_fmamk_f32 v64, v64, 0x3a800000, v158
	v_mul_f32_e32 v65, 0x4f800000, v64
	v_cmp_gt_f32_e32 vcc, s87, v64
	s_nop 1
	v_cndmask_b32_e32 v66, v64, v65, vcc
	v_sqrt_f32_e32 v67, v66
	v_lshl_add_u64 v[64:65], v[146:147], 0, s[20:21]
	v_add_u32_e32 v68, -1, v67
	v_add_u32_e32 v69, 1, v67
	v_fma_f32 v70, -v68, v67, v66
	v_fma_f32 v71, -v69, v67, v66
	v_cmp_ge_f32_e64 s[0:1], 0, v70
	s_nop 1
	v_cndmask_b32_e64 v67, v67, v68, s[0:1]
	v_cmp_lt_f32_e64 s[0:1], 0, v71
	s_nop 1
	v_cndmask_b32_e64 v67, v67, v69, s[0:1]
	v_mul_f32_e32 v68, 0x37800000, v67
	v_cndmask_b32_e32 v67, v67, v68, vcc
	v_cmp_class_f32_e32 vcc, v66, v159
	s_nop 1
	v_cndmask_b32_e32 v68, v67, v66, vcc
	v_div_scale_f32 v69, s[0:1], v68, v68, 1.0
	v_rcp_f32_e32 v70, v69
	v_add_co_u32_e32 v66, vcc, s88, v146
	v_fma_f32 v72, -v69, v70, 1.0
	s_nop 0
	v_addc_co_u32_e32 v67, vcc, 0, v147, vcc
	v_div_scale_f32 v71, vcc, 1.0, v68, 1.0
	v_fmac_f32_e32 v70, v72, v70
	v_mul_f32_e32 v72, v71, v70
	v_fma_f32 v73, -v69, v72, v71
	v_fmac_f32_e32 v72, v73, v70
	v_fma_f32 v69, -v69, v72, v71
	v_div_fmas_f32 v69, v69, v70, v72
	v_div_fixup_f32 v68, v69, v68, 1.0
	v_mul_f32_e32 v62, v62, v68
	v_mul_f32_e32 v63, v63, v68
	v_mul_f32_e32 v60, v60, v68
	v_mul_f32_e32 v61, v61, v68
	v_mul_f32_e32 v58, v58, v68
	v_mul_f32_e32 v59, v59, v68
	v_mul_f32_e32 v56, v56, v68
	v_mul_f32_e32 v57, v57, v68
	v_mul_f32_e32 v54, v54, v68
	v_mul_f32_e32 v55, v55, v68
	v_mul_f32_e32 v52, v52, v68
	v_mul_f32_e32 v53, v53, v68
	v_mul_f32_e32 v70, v50, v68
	v_mul_f32_e32 v71, v51, v68
	v_mul_f32_e32 v69, v49, v68
	v_mul_f32_e32 v68, v48, v68
	v_cvt_pk_bf16_f32 v48, v60, v61
	v_cvt_pk_bf16_f32 v49, v62, v63
	v_cvt_pk_bf16_f32 v50, v56, v57
	v_cvt_pk_bf16_f32 v51, v58, v59
	global_store_dwordx4 v[66:67], v[48:51], off
	s_nop 1
	v_cvt_pk_bf16_f32 v48, v52, v53
	v_cvt_pk_bf16_f32 v49, v54, v55
	v_cvt_pk_bf16_f32 v50, v68, v69
; __device__ __forceinline__ unsigned cvt_pk_bf16(float lo, float hi) { unsigned r; asm volatile("v_cvt_pk_bf16_f32 %0, %1, %2" : "=v"(r) : "v"(lo), "v"(hi)); return r; }
; #define PG8_BAR __builtin_amdgcn_s_barrier()
;     __device__ __forceinline__ void operator()(const f32x4 (&acc)[2][2][4][2], const Unit& u, int wr, int wc, int fr, int fq) const {
;     ...
;             for (int m = 0; m < 4; ++m) { const int row = row0 + ai * HALF + m * 16; bf16_t* rowp = O + (size_t)row * ldc + col0;
;                 float sc = sc0; if (ROWSCALE) sc *= 1.0f / sqrtf(SS[row] * (1.0f / 1024.0f) + 1e-6f);
; #pragma unroll
;                 for (int bj = 0; bj < 2; ++bj) { const f32x4 v0 = acc[ai][bj][m][0] * sc, v1 = acc[ai][bj][m][1] * sc;
;                     u32x4 w; w.x = cvt_pk_bf16(v0[0], v0[1]); w.y = cvt_pk_bf16(v0[2], v0[3]); w.z = cvt_pk_bf16(v1[0], v1[1]); w.w = cvt_pk_bf16(v1[2], v1[3]);
;                     *(u32x4*)(rowp + bj * HALF) = w; } }
; template <class Epi, class Sched, bool ALIGN_EPI = false, bool SP2 = false>
; __device__ __forceinline__ void gemm_phase(PG8_LAS unsigned char* lds, const Gemm g, const Sched& S, const Epi& E) {
;     ...
;         if constexpr (ALIGN_EPI) { if (wr == 0) PG8_BAR; }
;         if constexpr (!Epi::AFTER_DRAIN) { E(acc, cur, wr, wc, fr, fq); S.done(cur); }
;         if (!has_next) break;
; #pragma unroll
;         for (int a = 0; a < 2; ++a)
; #pragma unroll
;             for (int b = 0; b < 2; ++b)
; #pragma unroll
;                 for (int m = 0; m < 4; ++m)
; #pragma unroll
;                     for (int n = 0; n < 2; ++n) acc[a][b][m][n] = (f32x4){0.f, 0.f, 0.f, 0.f};
;         cur = nxt; cA = nA; cB = nB; ++ui;
;         if constexpr (ALIGN_EPI) { if (wr == 1) PG8_BAR; }
	v_cvt_pk_bf16_f32 v51, v70, v71
	global_store_dwordx4 v[64:65], v[48:51], off offset:256
	s_nop 1
	v_mov_b32_e32 v48, v235
	v_fmamk_f32 v48, v48, 0x3a800000, v158
	v_mul_f32_e32 v49, 0x4f800000, v48
	v_cmp_gt_f32_e32 vcc, s87, v48
	s_nop 1
	v_cndmask_b32_e32 v50, v48, v49, vcc
	v_sqrt_f32_e32 v51, v50
	v_lshl_add_u64 v[48:49], v[146:147], 0, s[38:39]
	v_add_u32_e32 v52, -1, v51
	v_add_u32_e32 v53, 1, v51
	v_fma_f32 v54, -v52, v51, v50
	v_fma_f32 v55, -v53, v51, v50
	v_cmp_ge_f32_e64 s[0:1], 0, v54
	s_nop 1
	v_cndmask_b32_e64 v51, v51, v52, s[0:1]
	v_cmp_lt_f32_e64 s[0:1], 0, v55
	s_nop 1
	v_cndmask_b32_e64 v51, v51, v53, s[0:1]
	v_mul_f32_e32 v52, 0x37800000, v51
	v_cndmask_b32_e32 v51, v51, v52, vcc
	v_cmp_class_f32_e32 vcc, v50, v159
	s_nop 1
	v_cndmask_b32_e32 v52, v51, v50, vcc
	v_div_scale_f32 v53, s[0:1], v52, v52, 1.0
	v_rcp_f32_e32 v54, v53
	v_add_co_u32_e32 v50, vcc, s89, v146
	v_fma_f32 v56, -v53, v54, 1.0
	s_nop 0
	v_addc_co_u32_e32 v51, vcc, 0, v147, vcc
	v_div_scale_f32 v55, vcc, 1.0, v52, 1.0
	v_fmac_f32_e32 v54, v56, v54
	v_mul_f32_e32 v56, v55, v54
	v_fma_f32 v57, -v53, v56, v55
	v_fmac_f32_e32 v56, v57, v54
	v_fma_f32 v53, -v53, v56, v55
	v_div_fmas_f32 v53, v53, v54, v56
	v_div_fixup_f32 v52, v53, v52, 1.0
	v_mul_f32_e32 v46, v46, v52
	v_mul_f32_e32 v47, v47, v52
	v_mul_f32_e32 v44, v44, v52
	v_mul_f32_e32 v45, v45, v52
	v_mul_f32_e32 v42, v42, v52
	v_mul_f32_e32 v43, v43, v52
	v_mul_f32_e32 v40, v40, v52
	v_mul_f32_e32 v41, v41, v52
	v_mul_f32_e32 v38, v38, v52
	v_mul_f32_e32 v39, v39, v52
	v_mul_f32_e32 v36, v36, v52
	v_mul_f32_e32 v37, v37, v52
	v_mul_f32_e32 v54, v34, v52
	v_mul_f32_e32 v55, v35, v52
	v_mul_f32_e32 v53, v33, v52
	v_mul_f32_e32 v52, v32, v52
	v_cvt_pk_bf16_f32 v32, v44, v45
	v_cvt_pk_bf16_f32 v33, v46, v47
	v_cvt_pk_bf16_f32 v34, v40, v41
	v_cvt_pk_bf16_f32 v35, v42, v43
	global_store_dwordx4 v[50:51], v[32:35], off
	s_nop 1
	v_cvt_pk_bf16_f32 v32, v36, v37
	v_cvt_pk_bf16_f32 v33, v38, v39
	v_cvt_pk_bf16_f32 v34, v52, v53
	v_cvt_pk_bf16_f32 v35, v54, v55
	global_store_dwordx4 v[48:49], v[32:35], off offset:256
	s_nop 1
	v_mov_b32_e32 v32, v236
	v_fmamk_f32 v32, v32, 0x3a800000, v158
	v_mul_f32_e32 v33, 0x4f800000, v32
	v_cmp_gt_f32_e32 vcc, s87, v32
	s_nop 1
	v_cndmask_b32_e32 v34, v32, v33, vcc
	v_sqrt_f32_e32 v35, v34
	v_lshl_add_u64 v[32:33], v[146:147], 0, s[42:43]
	v_add_u32_e32 v36, -1, v35
	v_add_u32_e32 v37, 1, v35
	v_fma_f32 v38, -v36, v35, v34
	v_fma_f32 v39, -v37, v35, v34
	v_cmp_ge_f32_e64 s[0:1], 0, v38
	s_nop 1
	v_cndmask_b32_e64 v35, v35, v36, s[0:1]
	v_cmp_lt_f32_e64 s[0:1], 0, v39
	s_nop 1
	v_cndmask_b32_e64 v35, v35, v37, s[0:1]
	v_mul_f32_e32 v36, 0x37800000, v35
	v_cndmask_b32_e32 v35, v35, v36, vcc
	v_cmp_class_f32_e32 vcc, v34, v159
	s_nop 1
	v_cndmask_b32_e32 v36, v35, v34, vcc
	v_div_scale_f32 v37, s[0:1], v36, v36, 1.0
	v_rcp_f32_e32 v38, v37
	v_add_co_u32_e32 v34, vcc, s90, v146
	v_fma_f32 v40, -v37, v38, 1.0
	s_nop 0
	v_addc_co_u32_e32 v35, vcc, 0, v147, vcc
	v_div_scale_f32 v39, vcc, 1.0, v36, 1.0
	v_fmac_f32_e32 v38, v40, v38
	v_mul_f32_e32 v40, v39, v38
	v_fma_f32 v41, -v37, v40, v39
	v_fmac_f32_e32 v40, v41, v38
	v_fma_f32 v37, -v37, v40, v39
	v_div_fmas_f32 v37, v37, v38, v40
	v_div_fixup_f32 v36, v37, v36, 1.0
	v_mul_f32_e32 v30, v30, v36
	v_mul_f32_e32 v31, v31, v36
	v_mul_f32_e32 v28, v28, v36
	v_mul_f32_e32 v29, v29, v36
	v_mul_f32_e32 v26, v26, v36
	v_mul_f32_e32 v27, v27, v36
	v_mul_f32_e32 v24, v24, v36
	v_mul_f32_e32 v25, v25, v36
	v_mul_f32_e32 v22, v22, v36
	v_mul_f32_e32 v23, v23, v36
	v_mul_f32_e32 v20, v20, v36
	v_mul_f32_e32 v21, v21, v36
	v_mul_f32_e32 v38, v18, v36
	v_mul_f32_e32 v39, v19, v36
	v_mul_f32_e32 v37, v17, v36
	v_mul_f32_e32 v36, v16, v36
	v_cvt_pk_bf16_f32 v16, v28, v29
	v_cvt_pk_bf16_f32 v17, v30, v31
	v_cvt_pk_bf16_f32 v18, v24, v25
	v_cvt_pk_bf16_f32 v19, v26, v27
	global_store_dwordx4 v[34:35], v[16:19], off
	s_nop 1
	v_cvt_pk_bf16_f32 v16, v20, v21
	v_cvt_pk_bf16_f32 v17, v22, v23
	v_cvt_pk_bf16_f32 v18, v36, v37
	v_cvt_pk_bf16_f32 v19, v38, v39
	global_store_dwordx4 v[32:33], v[16:19], off offset:256
	s_nop 1
	v_mov_b32_e32 v16, v237
	v_fmamk_f32 v16, v16, 0x3a800000, v158
	v_mul_f32_e32 v17, 0x4f800000, v16
	v_cmp_gt_f32_e32 vcc, s87, v16
	s_nop 1
	v_cndmask_b32_e32 v18, v16, v17, vcc
	v_sqrt_f32_e32 v19, v18
	v_lshl_add_u64 v[16:17], v[146:147], 0, s[48:49]
	v_add_u32_e32 v20, -1, v19
	v_add_u32_e32 v21, 1, v19
	v_fma_f32 v22, -v20, v19, v18
	v_fma_f32 v23, -v21, v19, v18
	v_cmp_ge_f32_e64 s[0:1], 0, v22
	s_nop 1
	v_cndmask_b32_e64 v19, v19, v20, s[0:1]
	v_cmp_lt_f32_e64 s[0:1], 0, v23
	s_nop 1
	v_cndmask_b32_e64 v19, v19, v21, s[0:1]
	v_mul_f32_e32 v20, 0x37800000, v19
	v_cndmask_b32_e32 v19, v19, v20, vcc
	v_cmp_class_f32_e32 vcc, v18, v159
	s_nop 1
	v_cndmask_b32_e32 v20, v19, v18, vcc
	v_div_scale_f32 v21, s[0:1], v20, v20, 1.0
	v_rcp_f32_e32 v22, v21
	v_add_co_u32_e32 v18, vcc, s91, v146
	s_mov_b64 s[0:1], -1
	s_nop 0
	v_addc_co_u32_e32 v19, vcc, 0, v147, vcc
	v_fma_f32 v24, -v21, v22, 1.0
	v_div_scale_f32 v23, vcc, 1.0, v20, 1.0
	v_fmac_f32_e32 v22, v24, v22
	v_mul_f32_e32 v24, v23, v22
	v_fma_f32 v25, -v21, v24, v23
	v_fmac_f32_e32 v24, v25, v22
	v_fma_f32 v21, -v21, v24, v23
	v_div_fmas_f32 v21, v21, v22, v24
	v_div_fixup_f32 v20, v21, v20, 1.0
	s_andn2_b64 vcc, exec, s[4:5]
	v_mul_f32_e32 v14, v14, v20
	v_mul_f32_e32 v15, v15, v20
	v_mul_f32_e32 v12, v12, v20
	v_mul_f32_e32 v13, v13, v20
	v_mul_f32_e32 v10, v10, v20
	v_mul_f32_e32 v11, v11, v20
	v_mul_f32_e32 v8, v8, v20
	v_mul_f32_e32 v9, v9, v20
	v_mul_f32_e32 v6, v6, v20
	v_mul_f32_e32 v7, v7, v20
	v_mul_f32_e32 v4, v4, v20
	v_mul_f32_e32 v5, v5, v20
	v_mul_f32_e32 v22, v2, v20
	v_mul_f32_e32 v23, v3, v20
	v_mul_f32_e32 v21, v1, v20
	v_mul_f32_e32 v20, v0, v20
	v_cvt_pk_bf16_f32 v0, v12, v13
	v_cvt_pk_bf16_f32 v1, v14, v15
	v_cvt_pk_bf16_f32 v2, v8, v9
	v_cvt_pk_bf16_f32 v3, v10, v11
	global_store_dwordx4 v[18:19], v[0:3], off
	s_nop 1
	v_cvt_pk_bf16_f32 v0, v4, v5
	v_cvt_pk_bf16_f32 v1, v6, v7
	v_cvt_pk_bf16_f32 v2, v20, v21
	v_cvt_pk_bf16_f32 v3, v22, v23
	global_store_dwordx4 v[16:17], v[0:3], off offset:256
	s_cbranch_vccnz .LBB0_926
	s_andn2_b64 vcc, exec, s[6:7]
	s_cbranch_vccnz .LBB0_925
	s_barrier
	s_branch .LBB0_925
